# final RMSNorm: hand-written fast path (32 rows per wave: gains loaded once, all rstd up front, 4-rows-ahead double-buffered nt loads) instead of the fully serialized compiler loop
# speedup vs baseline: 1.0170x; 1.0096x over previous
; __device__ __forceinline__ float bflo(unsigned w) { return __uint_as_float(w << 16); }
; __device__ __forceinline__ float bfhi(unsigned w) { return __uint_as_float(w & 0xffff0000u); }
; #define lane (hw_lane())
; __global__ void __launch_bounds__(512, 2) fwd_megakernel(Args a) {
;     ...
;     { const float* fg = a.in[I_FING]; const int ln = lane, gw0 = grouped ? grp * SEQ + gj * 256 + wave * 32 : gw, fstep = grouped ? 1 : NGW, flim = grouped ? gw0 + 32 : M;
;       v2u nw[4]; float nrs = 0.f;
;       if (gw0 < flim) { const v2u* xr = (const v2u*)(HB + (size_t)gw0 * D) + ln; nrs = pg8::row_rstd(slots, gw0);
; #pragma unroll
;         for (int j = 0; j < 4; ++j) nw[j] = __builtin_nontemporal_load(xr + 64 * j); }
;       for (int m = gw0; m < flim; m += fstep) { f32x4* orow = (f32x4*)(hres + (size_t)m * D) + ln;
;         v2u w[4]; const float rs = nrs;
; #pragma unroll
;         for (int j = 0; j < 4; ++j) w[j] = nw[j];
;         { const int mn = m + fstep; if (mn < flim) { const v2u* xr = (const v2u*)(HB + (size_t)mn * D) + ln; nrs = pg8::row_rstd(slots, mn);
; #pragma unroll
;             for (int j = 0; j < 4; ++j) nw[j] = __builtin_nontemporal_load(xr + 64 * j); } }
; #pragma unroll
;         for (int j = 0; j < 4; ++j) { const f32x4 gg = *((const f32x4*)fg + ln + 64 * j);
;             __builtin_nontemporal_store((f32x4){bflo(w[j].x), bfhi(w[j].x), bflo(w[j].y), bfhi(w[j].y)} * rs * gg, orow + 64 * j); } } }
.LBB0_1115:
	v_readlane_b32 s0, v253, 43
	s_add_i32 s2, s18, 32
	v_readlane_b32 s1, v253, 44
	s_and_b64 s[0:1], s[0:1], exec
	s_cselect_b32 s8, s2, 0x10000
	s_cmp_ge_i32 s18, s8
	s_cbranch_scc1 .LBB0_1120
	s_lshl_b32 s0, s16, 5
	s_add_i32 s0, s0, s18
	s_cmp_lt_i32 s0, s8
	s_cbranch_scc1 .Lfn_generic
	s_sub_i32 s1, s0, s16
	s_cmp_ge_i32 s1, s8
	s_cbranch_scc1 .Lfn_generic
	v_mul_lo_u32 v1, v0, s16
	s_add_u32 s2, s58, 0x5500000
	s_addc_u32 s3, s59, 0
	v_lshlrev_b32_e32 v2, 4, v0
	v_add_u32_e32 v1, s18, v1
	s_add_u32 s4, s58, 0x7100000
	s_addc_u32 s5, s59, 0
	v_lshlrev_b32_e32 v1, 6, v1
	v_lshlrev_b32_e32 v3, 3, v0
	s_lshl_b32 s6, s18, 11
	s_add_u32 s20, s4, s6
	s_addc_u32 s21, s5, 0
	s_lshl_b32 s6, s18, 12
	s_add_u32 s22, s56, s6
	s_addc_u32 s23, s57, 0
	s_lshl_b32 s24, s16, 11
	s_lshl_b32 s25, s16, 12
	global_load_dwordx4 v[16:19], v1, s[2:3]
	global_load_dwordx4 v[20:23], v1, s[2:3] offset:16
	global_load_dwordx4 v[24:27], v1, s[2:3] offset:32
	global_load_dwordx4 v[28:31], v1, s[2:3] offset:48
	global_load_dwordx4 v[32:35], v2, s[54:55]
	global_load_dwordx4 v[36:39], v2, s[54:55] offset:1024
	global_load_dwordx4 v[40:43], v2, s[54:55] offset:2048
	global_load_dwordx4 v[44:47], v2, s[54:55] offset:3072
	global_load_dwordx2 v[48:49], v3, s[20:21] nt
	global_load_dwordx2 v[50:51], v3, s[20:21] offset:512 nt
	global_load_dwordx2 v[52:53], v3, s[20:21] offset:1024 nt
	global_load_dwordx2 v[54:55], v3, s[20:21] offset:1536 nt
	s_add_u32 s20, s20, s24
	s_addc_u32 s21, s21, 0
	global_load_dwordx2 v[56:57], v3, s[20:21] nt
	global_load_dwordx2 v[58:59], v3, s[20:21] offset:512 nt
	global_load_dwordx2 v[60:61], v3, s[20:21] offset:1024 nt
	global_load_dwordx2 v[62:63], v3, s[20:21] offset:1536 nt
	s_add_u32 s20, s20, s24
	s_addc_u32 s21, s21, 0
	global_load_dwordx2 v[64:65], v3, s[20:21] nt
	global_load_dwordx2 v[66:67], v3, s[20:21] offset:512 nt
	global_load_dwordx2 v[68:69], v3, s[20:21] offset:1024 nt
	global_load_dwordx2 v[70:71], v3, s[20:21] offset:1536 nt
	s_add_u32 s20, s20, s24
	s_addc_u32 s21, s21, 0
	global_load_dwordx2 v[72:73], v3, s[20:21] nt
	global_load_dwordx2 v[74:75], v3, s[20:21] offset:512 nt
	global_load_dwordx2 v[76:77], v3, s[20:21] offset:1024 nt
	global_load_dwordx2 v[78:79], v3, s[20:21] offset:1536 nt
	s_add_u32 s20, s20, s24
	s_addc_u32 s21, s21, 0
	s_waitcnt vmcnt(20)
	v_pk_add_f32 v[18:19], v[18:19], v[22:23]
	v_pk_add_f32 v[16:17], v[16:17], v[20:21]
	v_pk_add_f32 v[20:21], v[26:27], v[30:31]
	v_pk_add_f32 v[22:23], v[24:25], v[28:29]
	v_pk_add_f32 v[18:19], v[18:19], v[20:21]
	v_pk_add_f32 v[16:17], v[16:17], v[22:23]
	v_mov_b32_e32 v28, 0x358637bd
	v_add_f32_e32 v16, v16, v17
	v_add_f32_e32 v17, v18, v19
	s_nop 0
	v_add_f32_e32 v16, v16, v17
	s_nop 0
	v_fmamk_f32 v16, v16, 0x3a800000, v28
	s_nop 0
	v_rsq_f32_e32 v16, v16
	global_load_dwordx2 v[80:81], v3, s[20:21] nt
	global_load_dwordx2 v[82:83], v3, s[20:21] offset:512 nt
	global_load_dwordx2 v[84:85], v3, s[20:21] offset:1024 nt
	global_load_dwordx2 v[86:87], v3, s[20:21] offset:1536 nt
	s_add_u32 s20, s20, s24
	s_addc_u32 s21, s21, 0
	global_load_dwordx2 v[88:89], v3, s[20:21] nt
	global_load_dwordx2 v[90:91], v3, s[20:21] offset:512 nt
	global_load_dwordx2 v[92:93], v3, s[20:21] offset:1024 nt
	global_load_dwordx2 v[94:95], v3, s[20:21] offset:1536 nt
	s_add_u32 s20, s20, s24
	s_addc_u32 s21, s21, 0
	global_load_dwordx2 v[96:97], v3, s[20:21] nt
	global_load_dwordx2 v[98:99], v3, s[20:21] offset:512 nt
	global_load_dwordx2 v[100:101], v3, s[20:21] offset:1024 nt
	global_load_dwordx2 v[102:103], v3, s[20:21] offset:1536 nt
	s_add_u32 s20, s20, s24
	s_addc_u32 s21, s21, 0
	global_load_dwordx2 v[104:105], v3, s[20:21] nt
	global_load_dwordx2 v[106:107], v3, s[20:21] offset:512 nt
	global_load_dwordx2 v[108:109], v3, s[20:21] offset:1024 nt
	global_load_dwordx2 v[110:111], v3, s[20:21] offset:1536 nt
	s_add_u32 s20, s20, s24
	s_addc_u32 s21, s21, 0
	s_waitcnt vmcnt(16)
	v_readlane_b32 s26, v16, 0
	v_lshlrev_b32_e32 v120, 16, v48
	v_and_b32_e32 v121, 0xffff0000, v48
	v_lshlrev_b32_e32 v122, 16, v49
	v_and_b32_e32 v123, 0xffff0000, v49
	v_mul_f32_e32 v120, s26, v120
	v_mul_f32_e32 v121, s26, v121
	v_mul_f32_e32 v122, s26, v122
	v_mul_f32_e32 v123, s26, v123
	v_mul_f32_e32 v124, v120, v32
	v_mul_f32_e32 v125, v121, v33
	v_mul_f32_e32 v126, v122, v34
	v_mul_f32_e32 v127, v123, v35
	global_store_dwordx4 v2, v[124:127], s[22:23] nt
	v_lshlrev_b32_e32 v120, 16, v50
	v_and_b32_e32 v121, 0xffff0000, v50
	v_lshlrev_b32_e32 v122, 16, v51
	v_and_b32_e32 v123, 0xffff0000, v51
	v_mul_f32_e32 v120, s26, v120
	v_mul_f32_e32 v121, s26, v121
	v_mul_f32_e32 v122, s26, v122
	v_mul_f32_e32 v123, s26, v123
	v_mul_f32_e32 v128, v120, v36
	v_mul_f32_e32 v129, v121, v37
	v_mul_f32_e32 v130, v122, v38
	v_mul_f32_e32 v131, v123, v39
	global_store_dwordx4 v2, v[128:131], s[22:23] offset:1024 nt
	v_lshlrev_b32_e32 v120, 16, v52
	v_and_b32_e32 v121, 0xffff0000, v52
	v_lshlrev_b32_e32 v122, 16, v53
	v_and_b32_e32 v123, 0xffff0000, v53
	v_mul_f32_e32 v120, s26, v120
	v_mul_f32_e32 v121, s26, v121
	v_mul_f32_e32 v122, s26, v122
	v_mul_f32_e32 v123, s26, v123
	v_mul_f32_e32 v132, v120, v40
	v_mul_f32_e32 v133, v121, v41
	v_mul_f32_e32 v134, v122, v42
	v_mul_f32_e32 v135, v123, v43
	global_store_dwordx4 v2, v[132:135], s[22:23] offset:2048 nt
	v_lshlrev_b32_e32 v120, 16, v54
	v_and_b32_e32 v121, 0xffff0000, v54
	v_lshlrev_b32_e32 v122, 16, v55
	v_and_b32_e32 v123, 0xffff0000, v55
	v_mul_f32_e32 v120, s26, v120
	v_mul_f32_e32 v121, s26, v121
	v_mul_f32_e32 v122, s26, v122
	v_mul_f32_e32 v123, s26, v123
	v_mul_f32_e32 v136, v120, v44
	v_mul_f32_e32 v137, v121, v45
	v_mul_f32_e32 v138, v122, v46
; __device__ __forceinline__ float bflo(unsigned w) { return __uint_as_float(w << 16); }
; __device__ __forceinline__ float bfhi(unsigned w) { return __uint_as_float(w & 0xffff0000u); }
; __global__ void __launch_bounds__(512, 2) fwd_megakernel(Args a) {
;     ...
;       for (int m = gw0; m < flim; m += fstep) { f32x4* orow = (f32x4*)(hres + (size_t)m * D) + ln;
;         v2u w[4]; const float rs = nrs;
; #pragma unroll
;         for (int j = 0; j < 4; ++j) w[j] = nw[j];
;         { const int mn = m + fstep; if (mn < flim) { const v2u* xr = (const v2u*)(HB + (size_t)mn * D) + ln; nrs = pg8::row_rstd(slots, mn);
; #pragma unroll
;             for (int j = 0; j < 4; ++j) nw[j] = __builtin_nontemporal_load(xr + 64 * j); } }
; #pragma unroll
;         for (int j = 0; j < 4; ++j) { const f32x4 gg = *((const f32x4*)fg + ln + 64 * j);
;             __builtin_nontemporal_store((f32x4){bflo(w[j].x), bfhi(w[j].x), bflo(w[j].y), bfhi(w[j].y)} * rs * gg, orow + 64 * j); } } }
	v_mul_f32_e32 v139, v123, v47
	global_store_dwordx4 v2, v[136:139], s[22:23] offset:3072 nt
	s_add_u32 s22, s22, s25
	s_addc_u32 s23, s23, 0
	v_readlane_b32 s26, v16, 1
	v_lshlrev_b32_e32 v120, 16, v56
	v_and_b32_e32 v121, 0xffff0000, v56
	v_lshlrev_b32_e32 v122, 16, v57
	v_and_b32_e32 v123, 0xffff0000, v57
	v_mul_f32_e32 v120, s26, v120
	v_mul_f32_e32 v121, s26, v121
	v_mul_f32_e32 v122, s26, v122
	v_mul_f32_e32 v123, s26, v123
	v_mul_f32_e32 v124, v120, v32
	v_mul_f32_e32 v125, v121, v33
	v_mul_f32_e32 v126, v122, v34
	v_mul_f32_e32 v127, v123, v35
	global_store_dwordx4 v2, v[124:127], s[22:23] nt
	v_lshlrev_b32_e32 v120, 16, v58
	v_and_b32_e32 v121, 0xffff0000, v58
	v_lshlrev_b32_e32 v122, 16, v59
	v_and_b32_e32 v123, 0xffff0000, v59
	v_mul_f32_e32 v120, s26, v120
	v_mul_f32_e32 v121, s26, v121
	v_mul_f32_e32 v122, s26, v122
	v_mul_f32_e32 v123, s26, v123
	v_mul_f32_e32 v128, v120, v36
	v_mul_f32_e32 v129, v121, v37
	v_mul_f32_e32 v130, v122, v38
	v_mul_f32_e32 v131, v123, v39
	global_store_dwordx4 v2, v[128:131], s[22:23] offset:1024 nt
	v_lshlrev_b32_e32 v120, 16, v60
	v_and_b32_e32 v121, 0xffff0000, v60
	v_lshlrev_b32_e32 v122, 16, v61
	v_and_b32_e32 v123, 0xffff0000, v61
	v_mul_f32_e32 v120, s26, v120
	v_mul_f32_e32 v121, s26, v121
	v_mul_f32_e32 v122, s26, v122
	v_mul_f32_e32 v123, s26, v123
	v_mul_f32_e32 v132, v120, v40
	v_mul_f32_e32 v133, v121, v41
	v_mul_f32_e32 v134, v122, v42
	v_mul_f32_e32 v135, v123, v43
	global_store_dwordx4 v2, v[132:135], s[22:23] offset:2048 nt
	v_lshlrev_b32_e32 v120, 16, v62
	v_and_b32_e32 v121, 0xffff0000, v62
	v_lshlrev_b32_e32 v122, 16, v63
	v_and_b32_e32 v123, 0xffff0000, v63
	v_mul_f32_e32 v120, s26, v120
	v_mul_f32_e32 v121, s26, v121
	v_mul_f32_e32 v122, s26, v122
	v_mul_f32_e32 v123, s26, v123
	v_mul_f32_e32 v136, v120, v44
	v_mul_f32_e32 v137, v121, v45
	v_mul_f32_e32 v138, v122, v46
	v_mul_f32_e32 v139, v123, v47
	global_store_dwordx4 v2, v[136:139], s[22:23] offset:3072 nt
	s_add_u32 s22, s22, s25
	s_addc_u32 s23, s23, 0
	v_readlane_b32 s26, v16, 2
	v_lshlrev_b32_e32 v120, 16, v64
	v_and_b32_e32 v121, 0xffff0000, v64
	v_lshlrev_b32_e32 v122, 16, v65
	v_and_b32_e32 v123, 0xffff0000, v65
	v_mul_f32_e32 v120, s26, v120
	v_mul_f32_e32 v121, s26, v121
	v_mul_f32_e32 v122, s26, v122
	v_mul_f32_e32 v123, s26, v123
	v_mul_f32_e32 v124, v120, v32
	v_mul_f32_e32 v125, v121, v33
	v_mul_f32_e32 v126, v122, v34
	v_mul_f32_e32 v127, v123, v35
	global_store_dwordx4 v2, v[124:127], s[22:23] nt
	v_lshlrev_b32_e32 v120, 16, v66
	v_and_b32_e32 v121, 0xffff0000, v66
	v_lshlrev_b32_e32 v122, 16, v67
	v_and_b32_e32 v123, 0xffff0000, v67
	v_mul_f32_e32 v120, s26, v120
	v_mul_f32_e32 v121, s26, v121
	v_mul_f32_e32 v122, s26, v122
	v_mul_f32_e32 v123, s26, v123
	v_mul_f32_e32 v128, v120, v36
	v_mul_f32_e32 v129, v121, v37
	v_mul_f32_e32 v130, v122, v38
	v_mul_f32_e32 v131, v123, v39
	global_store_dwordx4 v2, v[128:131], s[22:23] offset:1024 nt
	v_lshlrev_b32_e32 v120, 16, v68
	v_and_b32_e32 v121, 0xffff0000, v68
	v_lshlrev_b32_e32 v122, 16, v69
	v_and_b32_e32 v123, 0xffff0000, v69
	v_mul_f32_e32 v120, s26, v120
	v_mul_f32_e32 v121, s26, v121
	v_mul_f32_e32 v122, s26, v122
	v_mul_f32_e32 v123, s26, v123
	v_mul_f32_e32 v132, v120, v40
	v_mul_f32_e32 v133, v121, v41
	v_mul_f32_e32 v134, v122, v42
	v_mul_f32_e32 v135, v123, v43
	global_store_dwordx4 v2, v[132:135], s[22:23] offset:2048 nt
	v_lshlrev_b32_e32 v120, 16, v70
	v_and_b32_e32 v121, 0xffff0000, v70
	v_lshlrev_b32_e32 v122, 16, v71
	v_and_b32_e32 v123, 0xffff0000, v71
	v_mul_f32_e32 v120, s26, v120
	v_mul_f32_e32 v121, s26, v121
	v_mul_f32_e32 v122, s26, v122
	v_mul_f32_e32 v123, s26, v123
	v_mul_f32_e32 v136, v120, v44
	v_mul_f32_e32 v137, v121, v45
	v_mul_f32_e32 v138, v122, v46
	v_mul_f32_e32 v139, v123, v47
	global_store_dwordx4 v2, v[136:139], s[22:23] offset:3072 nt
	s_add_u32 s22, s22, s25
	s_addc_u32 s23, s23, 0
	v_readlane_b32 s26, v16, 3
	v_lshlrev_b32_e32 v120, 16, v72
	v_and_b32_e32 v121, 0xffff0000, v72
	v_lshlrev_b32_e32 v122, 16, v73
	v_and_b32_e32 v123, 0xffff0000, v73
	v_mul_f32_e32 v120, s26, v120
	v_mul_f32_e32 v121, s26, v121
	v_mul_f32_e32 v122, s26, v122
	v_mul_f32_e32 v123, s26, v123
	v_mul_f32_e32 v124, v120, v32
	v_mul_f32_e32 v125, v121, v33
	v_mul_f32_e32 v126, v122, v34
	v_mul_f32_e32 v127, v123, v35
	global_store_dwordx4 v2, v[124:127], s[22:23] nt
	v_lshlrev_b32_e32 v120, 16, v74
	v_and_b32_e32 v121, 0xffff0000, v74
	v_lshlrev_b32_e32 v122, 16, v75
	v_and_b32_e32 v123, 0xffff0000, v75
	v_mul_f32_e32 v120, s26, v120
	v_mul_f32_e32 v121, s26, v121
	v_mul_f32_e32 v122, s26, v122
	v_mul_f32_e32 v123, s26, v123
	v_mul_f32_e32 v128, v120, v36
	v_mul_f32_e32 v129, v121, v37
	v_mul_f32_e32 v130, v122, v38
	v_mul_f32_e32 v131, v123, v39
	global_store_dwordx4 v2, v[128:131], s[22:23] offset:1024 nt
	v_lshlrev_b32_e32 v120, 16, v76
	v_and_b32_e32 v121, 0xffff0000, v76
	v_lshlrev_b32_e32 v122, 16, v77
	v_and_b32_e32 v123, 0xffff0000, v77
	v_mul_f32_e32 v120, s26, v120
	v_mul_f32_e32 v121, s26, v121
	v_mul_f32_e32 v122, s26, v122
	v_mul_f32_e32 v123, s26, v123
	v_mul_f32_e32 v132, v120, v40
	v_mul_f32_e32 v133, v121, v41
	v_mul_f32_e32 v134, v122, v42
	v_mul_f32_e32 v135, v123, v43
	global_store_dwordx4 v2, v[132:135], s[22:23] offset:2048 nt
	v_lshlrev_b32_e32 v120, 16, v78
	v_and_b32_e32 v121, 0xffff0000, v78
	v_lshlrev_b32_e32 v122, 16, v79
	v_and_b32_e32 v123, 0xffff0000, v79
	v_mul_f32_e32 v120, s26, v120
	v_mul_f32_e32 v121, s26, v121
	v_mul_f32_e32 v122, s26, v122
	v_mul_f32_e32 v123, s26, v123
	v_mul_f32_e32 v136, v120, v44
	v_mul_f32_e32 v137, v121, v45
	v_mul_f32_e32 v138, v122, v46
	v_mul_f32_e32 v139, v123, v47
	global_store_dwordx4 v2, v[136:139], s[22:23] offset:3072 nt
	s_add_u32 s22, s22, s25
	s_addc_u32 s23, s23, 0
	global_load_dwordx2 v[48:49], v3, s[20:21] nt
	global_load_dwordx2 v[50:51], v3, s[20:21] offset:512 nt
	global_load_dwordx2 v[52:53], v3, s[20:21] offset:1024 nt
	global_load_dwordx2 v[54:55], v3, s[20:21] offset:1536 nt
	s_add_u32 s20, s20, s24
	s_addc_u32 s21, s21, 0
	global_load_dwordx2 v[56:57], v3, s[20:21] nt
	global_load_dwordx2 v[58:59], v3, s[20:21] offset:512 nt
	global_load_dwordx2 v[60:61], v3, s[20:21] offset:1024 nt
	global_load_dwordx2 v[62:63], v3, s[20:21] offset:1536 nt
	s_add_u32 s20, s20, s24
	s_addc_u32 s21, s21, 0
	global_load_dwordx2 v[64:65], v3, s[20:21] nt
	global_load_dwordx2 v[66:67], v3, s[20:21] offset:512 nt
	global_load_dwordx2 v[68:69], v3, s[20:21] offset:1024 nt
	global_load_dwordx2 v[70:71], v3, s[20:21] offset:1536 nt
	s_add_u32 s20, s20, s24
	s_addc_u32 s21, s21, 0
	global_load_dwordx2 v[72:73], v3, s[20:21] nt
	global_load_dwordx2 v[74:75], v3, s[20:21] offset:512 nt
	global_load_dwordx2 v[76:77], v3, s[20:21] offset:1024 nt
	global_load_dwordx2 v[78:79], v3, s[20:21] offset:1536 nt
	s_add_u32 s20, s20, s24
	s_addc_u32 s21, s21, 0
	s_waitcnt vmcnt(32)
; __device__ __forceinline__ float bflo(unsigned w) { return __uint_as_float(w << 16); }
; __device__ __forceinline__ float bfhi(unsigned w) { return __uint_as_float(w & 0xffff0000u); }
; __global__ void __launch_bounds__(512, 2) fwd_megakernel(Args a) {
;     ...
;       for (int m = gw0; m < flim; m += fstep) { f32x4* orow = (f32x4*)(hres + (size_t)m * D) + ln;
;         v2u w[4]; const float rs = nrs;
; #pragma unroll
;         for (int j = 0; j < 4; ++j) w[j] = nw[j];
;         { const int mn = m + fstep; if (mn < flim) { const v2u* xr = (const v2u*)(HB + (size_t)mn * D) + ln; nrs = pg8::row_rstd(slots, mn);
; #pragma unroll
;             for (int j = 0; j < 4; ++j) nw[j] = __builtin_nontemporal_load(xr + 64 * j); } }
; #pragma unroll
;         for (int j = 0; j < 4; ++j) { const f32x4 gg = *((const f32x4*)fg + ln + 64 * j);
;             __builtin_nontemporal_store((f32x4){bflo(w[j].x), bfhi(w[j].x), bflo(w[j].y), bfhi(w[j].y)} * rs * gg, orow + 64 * j); } } }
	v_readlane_b32 s26, v16, 4
	v_lshlrev_b32_e32 v120, 16, v80
	v_and_b32_e32 v121, 0xffff0000, v80
	v_lshlrev_b32_e32 v122, 16, v81
	v_and_b32_e32 v123, 0xffff0000, v81
	v_mul_f32_e32 v120, s26, v120
	v_mul_f32_e32 v121, s26, v121
	v_mul_f32_e32 v122, s26, v122
	v_mul_f32_e32 v123, s26, v123
	v_mul_f32_e32 v124, v120, v32
	v_mul_f32_e32 v125, v121, v33
	v_mul_f32_e32 v126, v122, v34
	v_mul_f32_e32 v127, v123, v35
	global_store_dwordx4 v2, v[124:127], s[22:23] nt
	v_lshlrev_b32_e32 v120, 16, v82
	v_and_b32_e32 v121, 0xffff0000, v82
	v_lshlrev_b32_e32 v122, 16, v83
	v_and_b32_e32 v123, 0xffff0000, v83
	v_mul_f32_e32 v120, s26, v120
	v_mul_f32_e32 v121, s26, v121
	v_mul_f32_e32 v122, s26, v122
	v_mul_f32_e32 v123, s26, v123
	v_mul_f32_e32 v128, v120, v36
	v_mul_f32_e32 v129, v121, v37
	v_mul_f32_e32 v130, v122, v38
	v_mul_f32_e32 v131, v123, v39
	global_store_dwordx4 v2, v[128:131], s[22:23] offset:1024 nt
	v_lshlrev_b32_e32 v120, 16, v84
	v_and_b32_e32 v121, 0xffff0000, v84
	v_lshlrev_b32_e32 v122, 16, v85
	v_and_b32_e32 v123, 0xffff0000, v85
	v_mul_f32_e32 v120, s26, v120
	v_mul_f32_e32 v121, s26, v121
	v_mul_f32_e32 v122, s26, v122
	v_mul_f32_e32 v123, s26, v123
	v_mul_f32_e32 v132, v120, v40
	v_mul_f32_e32 v133, v121, v41
	v_mul_f32_e32 v134, v122, v42
	v_mul_f32_e32 v135, v123, v43
	global_store_dwordx4 v2, v[132:135], s[22:23] offset:2048 nt
	v_lshlrev_b32_e32 v120, 16, v86
	v_and_b32_e32 v121, 0xffff0000, v86
	v_lshlrev_b32_e32 v122, 16, v87
	v_and_b32_e32 v123, 0xffff0000, v87
	v_mul_f32_e32 v120, s26, v120
	v_mul_f32_e32 v121, s26, v121
	v_mul_f32_e32 v122, s26, v122
	v_mul_f32_e32 v123, s26, v123
	v_mul_f32_e32 v136, v120, v44
	v_mul_f32_e32 v137, v121, v45
	v_mul_f32_e32 v138, v122, v46
	v_mul_f32_e32 v139, v123, v47
	global_store_dwordx4 v2, v[136:139], s[22:23] offset:3072 nt
	s_add_u32 s22, s22, s25
	s_addc_u32 s23, s23, 0
	v_readlane_b32 s26, v16, 5
	v_lshlrev_b32_e32 v120, 16, v88
	v_and_b32_e32 v121, 0xffff0000, v88
	v_lshlrev_b32_e32 v122, 16, v89
	v_and_b32_e32 v123, 0xffff0000, v89
	v_mul_f32_e32 v120, s26, v120
	v_mul_f32_e32 v121, s26, v121
	v_mul_f32_e32 v122, s26, v122
	v_mul_f32_e32 v123, s26, v123
	v_mul_f32_e32 v124, v120, v32
	v_mul_f32_e32 v125, v121, v33
	v_mul_f32_e32 v126, v122, v34
	v_mul_f32_e32 v127, v123, v35
	global_store_dwordx4 v2, v[124:127], s[22:23] nt
	v_lshlrev_b32_e32 v120, 16, v90
	v_and_b32_e32 v121, 0xffff0000, v90
	v_lshlrev_b32_e32 v122, 16, v91
	v_and_b32_e32 v123, 0xffff0000, v91
	v_mul_f32_e32 v120, s26, v120
	v_mul_f32_e32 v121, s26, v121
	v_mul_f32_e32 v122, s26, v122
	v_mul_f32_e32 v123, s26, v123
	v_mul_f32_e32 v128, v120, v36
	v_mul_f32_e32 v129, v121, v37
	v_mul_f32_e32 v130, v122, v38
	v_mul_f32_e32 v131, v123, v39
	global_store_dwordx4 v2, v[128:131], s[22:23] offset:1024 nt
	v_lshlrev_b32_e32 v120, 16, v92
	v_and_b32_e32 v121, 0xffff0000, v92
	v_lshlrev_b32_e32 v122, 16, v93
	v_and_b32_e32 v123, 0xffff0000, v93
	v_mul_f32_e32 v120, s26, v120
	v_mul_f32_e32 v121, s26, v121
	v_mul_f32_e32 v122, s26, v122
	v_mul_f32_e32 v123, s26, v123
	v_mul_f32_e32 v132, v120, v40
	v_mul_f32_e32 v133, v121, v41
	v_mul_f32_e32 v134, v122, v42
	v_mul_f32_e32 v135, v123, v43
	global_store_dwordx4 v2, v[132:135], s[22:23] offset:2048 nt
	v_lshlrev_b32_e32 v120, 16, v94
	v_and_b32_e32 v121, 0xffff0000, v94
	v_lshlrev_b32_e32 v122, 16, v95
	v_and_b32_e32 v123, 0xffff0000, v95
	v_mul_f32_e32 v120, s26, v120
	v_mul_f32_e32 v121, s26, v121
	v_mul_f32_e32 v122, s26, v122
	v_mul_f32_e32 v123, s26, v123
	v_mul_f32_e32 v136, v120, v44
	v_mul_f32_e32 v137, v121, v45
	v_mul_f32_e32 v138, v122, v46
	v_mul_f32_e32 v139, v123, v47
	global_store_dwordx4 v2, v[136:139], s[22:23] offset:3072 nt
	s_add_u32 s22, s22, s25
	s_addc_u32 s23, s23, 0
	v_readlane_b32 s26, v16, 6
	v_lshlrev_b32_e32 v120, 16, v96
	v_and_b32_e32 v121, 0xffff0000, v96
	v_lshlrev_b32_e32 v122, 16, v97
	v_and_b32_e32 v123, 0xffff0000, v97
	v_mul_f32_e32 v120, s26, v120
	v_mul_f32_e32 v121, s26, v121
	v_mul_f32_e32 v122, s26, v122
	v_mul_f32_e32 v123, s26, v123
	v_mul_f32_e32 v124, v120, v32
	v_mul_f32_e32 v125, v121, v33
	v_mul_f32_e32 v126, v122, v34
	v_mul_f32_e32 v127, v123, v35
	global_store_dwordx4 v2, v[124:127], s[22:23] nt
	v_lshlrev_b32_e32 v120, 16, v98
	v_and_b32_e32 v121, 0xffff0000, v98
	v_lshlrev_b32_e32 v122, 16, v99
	v_and_b32_e32 v123, 0xffff0000, v99
	v_mul_f32_e32 v120, s26, v120
	v_mul_f32_e32 v121, s26, v121
	v_mul_f32_e32 v122, s26, v122
	v_mul_f32_e32 v123, s26, v123
	v_mul_f32_e32 v128, v120, v36
	v_mul_f32_e32 v129, v121, v37
	v_mul_f32_e32 v130, v122, v38
	v_mul_f32_e32 v131, v123, v39
	global_store_dwordx4 v2, v[128:131], s[22:23] offset:1024 nt
	v_lshlrev_b32_e32 v120, 16, v100
	v_and_b32_e32 v121, 0xffff0000, v100
	v_lshlrev_b32_e32 v122, 16, v101
	v_and_b32_e32 v123, 0xffff0000, v101
	v_mul_f32_e32 v120, s26, v120
	v_mul_f32_e32 v121, s26, v121
	v_mul_f32_e32 v122, s26, v122
	v_mul_f32_e32 v123, s26, v123
	v_mul_f32_e32 v132, v120, v40
	v_mul_f32_e32 v133, v121, v41
	v_mul_f32_e32 v134, v122, v42
	v_mul_f32_e32 v135, v123, v43
	global_store_dwordx4 v2, v[132:135], s[22:23] offset:2048 nt
	v_lshlrev_b32_e32 v120, 16, v102
	v_and_b32_e32 v121, 0xffff0000, v102
	v_lshlrev_b32_e32 v122, 16, v103
	v_and_b32_e32 v123, 0xffff0000, v103
	v_mul_f32_e32 v120, s26, v120
	v_mul_f32_e32 v121, s26, v121
	v_mul_f32_e32 v122, s26, v122
	v_mul_f32_e32 v123, s26, v123
	v_mul_f32_e32 v136, v120, v44
	v_mul_f32_e32 v137, v121, v45
	v_mul_f32_e32 v138, v122, v46
	v_mul_f32_e32 v139, v123, v47
	global_store_dwordx4 v2, v[136:139], s[22:23] offset:3072 nt
	s_add_u32 s22, s22, s25
	s_addc_u32 s23, s23, 0
	v_readlane_b32 s26, v16, 7
; __device__ __forceinline__ float bflo(unsigned w) { return __uint_as_float(w << 16); }
; __device__ __forceinline__ float bfhi(unsigned w) { return __uint_as_float(w & 0xffff0000u); }
; __global__ void __launch_bounds__(512, 2) fwd_megakernel(Args a) {
;     ...
;       for (int m = gw0; m < flim; m += fstep) { f32x4* orow = (f32x4*)(hres + (size_t)m * D) + ln;
;         v2u w[4]; const float rs = nrs;
; #pragma unroll
;         for (int j = 0; j < 4; ++j) w[j] = nw[j];
;         { const int mn = m + fstep; if (mn < flim) { const v2u* xr = (const v2u*)(HB + (size_t)mn * D) + ln; nrs = pg8::row_rstd(slots, mn);
; #pragma unroll
;             for (int j = 0; j < 4; ++j) nw[j] = __builtin_nontemporal_load(xr + 64 * j); } }
; #pragma unroll
;         for (int j = 0; j < 4; ++j) { const f32x4 gg = *((const f32x4*)fg + ln + 64 * j);
;             __builtin_nontemporal_store((f32x4){bflo(w[j].x), bfhi(w[j].x), bflo(w[j].y), bfhi(w[j].y)} * rs * gg, orow + 64 * j); } } }
	v_lshlrev_b32_e32 v120, 16, v104
	v_and_b32_e32 v121, 0xffff0000, v104
	v_lshlrev_b32_e32 v122, 16, v105
	v_and_b32_e32 v123, 0xffff0000, v105
	v_mul_f32_e32 v120, s26, v120
	v_mul_f32_e32 v121, s26, v121
	v_mul_f32_e32 v122, s26, v122
	v_mul_f32_e32 v123, s26, v123
	v_mul_f32_e32 v124, v120, v32
	v_mul_f32_e32 v125, v121, v33
	v_mul_f32_e32 v126, v122, v34
	v_mul_f32_e32 v127, v123, v35
	global_store_dwordx4 v2, v[124:127], s[22:23] nt
	v_lshlrev_b32_e32 v120, 16, v106
	v_and_b32_e32 v121, 0xffff0000, v106
	v_lshlrev_b32_e32 v122, 16, v107
	v_and_b32_e32 v123, 0xffff0000, v107
	v_mul_f32_e32 v120, s26, v120
	v_mul_f32_e32 v121, s26, v121
	v_mul_f32_e32 v122, s26, v122
	v_mul_f32_e32 v123, s26, v123
	v_mul_f32_e32 v128, v120, v36
	v_mul_f32_e32 v129, v121, v37
	v_mul_f32_e32 v130, v122, v38
	v_mul_f32_e32 v131, v123, v39
	global_store_dwordx4 v2, v[128:131], s[22:23] offset:1024 nt
	v_lshlrev_b32_e32 v120, 16, v108
	v_and_b32_e32 v121, 0xffff0000, v108
	v_lshlrev_b32_e32 v122, 16, v109
	v_and_b32_e32 v123, 0xffff0000, v109
	v_mul_f32_e32 v120, s26, v120
	v_mul_f32_e32 v121, s26, v121
	v_mul_f32_e32 v122, s26, v122
	v_mul_f32_e32 v123, s26, v123
	v_mul_f32_e32 v132, v120, v40
	v_mul_f32_e32 v133, v121, v41
	v_mul_f32_e32 v134, v122, v42
	v_mul_f32_e32 v135, v123, v43
	global_store_dwordx4 v2, v[132:135], s[22:23] offset:2048 nt
	v_lshlrev_b32_e32 v120, 16, v110
	v_and_b32_e32 v121, 0xffff0000, v110
	v_lshlrev_b32_e32 v122, 16, v111
	v_and_b32_e32 v123, 0xffff0000, v111
	v_mul_f32_e32 v120, s26, v120
	v_mul_f32_e32 v121, s26, v121
	v_mul_f32_e32 v122, s26, v122
	v_mul_f32_e32 v123, s26, v123
	v_mul_f32_e32 v136, v120, v44
	v_mul_f32_e32 v137, v121, v45
	v_mul_f32_e32 v138, v122, v46
	v_mul_f32_e32 v139, v123, v47
	global_store_dwordx4 v2, v[136:139], s[22:23] offset:3072 nt
	s_add_u32 s22, s22, s25
	s_addc_u32 s23, s23, 0
	global_load_dwordx2 v[80:81], v3, s[20:21] nt
	global_load_dwordx2 v[82:83], v3, s[20:21] offset:512 nt
	global_load_dwordx2 v[84:85], v3, s[20:21] offset:1024 nt
	global_load_dwordx2 v[86:87], v3, s[20:21] offset:1536 nt
	s_add_u32 s20, s20, s24
	s_addc_u32 s21, s21, 0
	global_load_dwordx2 v[88:89], v3, s[20:21] nt
	global_load_dwordx2 v[90:91], v3, s[20:21] offset:512 nt
	global_load_dwordx2 v[92:93], v3, s[20:21] offset:1024 nt
	global_load_dwordx2 v[94:95], v3, s[20:21] offset:1536 nt
	s_add_u32 s20, s20, s24
	s_addc_u32 s21, s21, 0
	global_load_dwordx2 v[96:97], v3, s[20:21] nt
	global_load_dwordx2 v[98:99], v3, s[20:21] offset:512 nt
	global_load_dwordx2 v[100:101], v3, s[20:21] offset:1024 nt
	global_load_dwordx2 v[102:103], v3, s[20:21] offset:1536 nt
	s_add_u32 s20, s20, s24
	s_addc_u32 s21, s21, 0
	global_load_dwordx2 v[104:105], v3, s[20:21] nt
	global_load_dwordx2 v[106:107], v3, s[20:21] offset:512 nt
	global_load_dwordx2 v[108:109], v3, s[20:21] offset:1024 nt
	global_load_dwordx2 v[110:111], v3, s[20:21] offset:1536 nt
	s_add_u32 s20, s20, s24
	s_addc_u32 s21, s21, 0
	s_waitcnt vmcnt(32)
	v_readlane_b32 s26, v16, 8
	v_lshlrev_b32_e32 v120, 16, v48
	v_and_b32_e32 v121, 0xffff0000, v48
	v_lshlrev_b32_e32 v122, 16, v49
	v_and_b32_e32 v123, 0xffff0000, v49
	v_mul_f32_e32 v120, s26, v120
	v_mul_f32_e32 v121, s26, v121
	v_mul_f32_e32 v122, s26, v122
	v_mul_f32_e32 v123, s26, v123
	v_mul_f32_e32 v124, v120, v32
	v_mul_f32_e32 v125, v121, v33
	v_mul_f32_e32 v126, v122, v34
	v_mul_f32_e32 v127, v123, v35
	global_store_dwordx4 v2, v[124:127], s[22:23] nt
	v_lshlrev_b32_e32 v120, 16, v50
	v_and_b32_e32 v121, 0xffff0000, v50
	v_lshlrev_b32_e32 v122, 16, v51
	v_and_b32_e32 v123, 0xffff0000, v51
	v_mul_f32_e32 v120, s26, v120
	v_mul_f32_e32 v121, s26, v121
	v_mul_f32_e32 v122, s26, v122
	v_mul_f32_e32 v123, s26, v123
	v_mul_f32_e32 v128, v120, v36
	v_mul_f32_e32 v129, v121, v37
	v_mul_f32_e32 v130, v122, v38
	v_mul_f32_e32 v131, v123, v39
	global_store_dwordx4 v2, v[128:131], s[22:23] offset:1024 nt
	v_lshlrev_b32_e32 v120, 16, v52
	v_and_b32_e32 v121, 0xffff0000, v52
	v_lshlrev_b32_e32 v122, 16, v53
	v_and_b32_e32 v123, 0xffff0000, v53
	v_mul_f32_e32 v120, s26, v120
	v_mul_f32_e32 v121, s26, v121
	v_mul_f32_e32 v122, s26, v122
	v_mul_f32_e32 v123, s26, v123
	v_mul_f32_e32 v132, v120, v40
	v_mul_f32_e32 v133, v121, v41
	v_mul_f32_e32 v134, v122, v42
	v_mul_f32_e32 v135, v123, v43
	global_store_dwordx4 v2, v[132:135], s[22:23] offset:2048 nt
	v_lshlrev_b32_e32 v120, 16, v54
	v_and_b32_e32 v121, 0xffff0000, v54
	v_lshlrev_b32_e32 v122, 16, v55
	v_and_b32_e32 v123, 0xffff0000, v55
	v_mul_f32_e32 v120, s26, v120
	v_mul_f32_e32 v121, s26, v121
	v_mul_f32_e32 v122, s26, v122
	v_mul_f32_e32 v123, s26, v123
	v_mul_f32_e32 v136, v120, v44
	v_mul_f32_e32 v137, v121, v45
	v_mul_f32_e32 v138, v122, v46
	v_mul_f32_e32 v139, v123, v47
	global_store_dwordx4 v2, v[136:139], s[22:23] offset:3072 nt
	s_add_u32 s22, s22, s25
	s_addc_u32 s23, s23, 0
	v_readlane_b32 s26, v16, 9
	v_lshlrev_b32_e32 v120, 16, v56
	v_and_b32_e32 v121, 0xffff0000, v56
	v_lshlrev_b32_e32 v122, 16, v57
	v_and_b32_e32 v123, 0xffff0000, v57
	v_mul_f32_e32 v120, s26, v120
	v_mul_f32_e32 v121, s26, v121
	v_mul_f32_e32 v122, s26, v122
	v_mul_f32_e32 v123, s26, v123
	v_mul_f32_e32 v124, v120, v32
	v_mul_f32_e32 v125, v121, v33
	v_mul_f32_e32 v126, v122, v34
	v_mul_f32_e32 v127, v123, v35
	global_store_dwordx4 v2, v[124:127], s[22:23] nt
	v_lshlrev_b32_e32 v120, 16, v58
	v_and_b32_e32 v121, 0xffff0000, v58
	v_lshlrev_b32_e32 v122, 16, v59
	v_and_b32_e32 v123, 0xffff0000, v59
	v_mul_f32_e32 v120, s26, v120
	v_mul_f32_e32 v121, s26, v121
	v_mul_f32_e32 v122, s26, v122
	v_mul_f32_e32 v123, s26, v123
	v_mul_f32_e32 v128, v120, v36
	v_mul_f32_e32 v129, v121, v37
; __device__ __forceinline__ float bflo(unsigned w) { return __uint_as_float(w << 16); }
; __device__ __forceinline__ float bfhi(unsigned w) { return __uint_as_float(w & 0xffff0000u); }
; __global__ void __launch_bounds__(512, 2) fwd_megakernel(Args a) {
;     ...
;       for (int m = gw0; m < flim; m += fstep) { f32x4* orow = (f32x4*)(hres + (size_t)m * D) + ln;
;         v2u w[4]; const float rs = nrs;
; #pragma unroll
;         for (int j = 0; j < 4; ++j) w[j] = nw[j];
;         { const int mn = m + fstep; if (mn < flim) { const v2u* xr = (const v2u*)(HB + (size_t)mn * D) + ln; nrs = pg8::row_rstd(slots, mn);
; #pragma unroll
;             for (int j = 0; j < 4; ++j) nw[j] = __builtin_nontemporal_load(xr + 64 * j); } }
; #pragma unroll
;         for (int j = 0; j < 4; ++j) { const f32x4 gg = *((const f32x4*)fg + ln + 64 * j);
;             __builtin_nontemporal_store((f32x4){bflo(w[j].x), bfhi(w[j].x), bflo(w[j].y), bfhi(w[j].y)} * rs * gg, orow + 64 * j); } } }
	v_mul_f32_e32 v130, v122, v38
	v_mul_f32_e32 v131, v123, v39
	global_store_dwordx4 v2, v[128:131], s[22:23] offset:1024 nt
	v_lshlrev_b32_e32 v120, 16, v60
	v_and_b32_e32 v121, 0xffff0000, v60
	v_lshlrev_b32_e32 v122, 16, v61
	v_and_b32_e32 v123, 0xffff0000, v61
	v_mul_f32_e32 v120, s26, v120
	v_mul_f32_e32 v121, s26, v121
	v_mul_f32_e32 v122, s26, v122
	v_mul_f32_e32 v123, s26, v123
	v_mul_f32_e32 v132, v120, v40
	v_mul_f32_e32 v133, v121, v41
	v_mul_f32_e32 v134, v122, v42
	v_mul_f32_e32 v135, v123, v43
	global_store_dwordx4 v2, v[132:135], s[22:23] offset:2048 nt
	v_lshlrev_b32_e32 v120, 16, v62
	v_and_b32_e32 v121, 0xffff0000, v62
	v_lshlrev_b32_e32 v122, 16, v63
	v_and_b32_e32 v123, 0xffff0000, v63
	v_mul_f32_e32 v120, s26, v120
	v_mul_f32_e32 v121, s26, v121
	v_mul_f32_e32 v122, s26, v122
	v_mul_f32_e32 v123, s26, v123
	v_mul_f32_e32 v136, v120, v44
	v_mul_f32_e32 v137, v121, v45
	v_mul_f32_e32 v138, v122, v46
	v_mul_f32_e32 v139, v123, v47
	global_store_dwordx4 v2, v[136:139], s[22:23] offset:3072 nt
	s_add_u32 s22, s22, s25
	s_addc_u32 s23, s23, 0
	v_readlane_b32 s26, v16, 10
	v_lshlrev_b32_e32 v120, 16, v64
	v_and_b32_e32 v121, 0xffff0000, v64
	v_lshlrev_b32_e32 v122, 16, v65
	v_and_b32_e32 v123, 0xffff0000, v65
	v_mul_f32_e32 v120, s26, v120
	v_mul_f32_e32 v121, s26, v121
	v_mul_f32_e32 v122, s26, v122
	v_mul_f32_e32 v123, s26, v123
	v_mul_f32_e32 v124, v120, v32
	v_mul_f32_e32 v125, v121, v33
	v_mul_f32_e32 v126, v122, v34
	v_mul_f32_e32 v127, v123, v35
	global_store_dwordx4 v2, v[124:127], s[22:23] nt
	v_lshlrev_b32_e32 v120, 16, v66
	v_and_b32_e32 v121, 0xffff0000, v66
	v_lshlrev_b32_e32 v122, 16, v67
	v_and_b32_e32 v123, 0xffff0000, v67
	v_mul_f32_e32 v120, s26, v120
	v_mul_f32_e32 v121, s26, v121
	v_mul_f32_e32 v122, s26, v122
	v_mul_f32_e32 v123, s26, v123
	v_mul_f32_e32 v128, v120, v36
	v_mul_f32_e32 v129, v121, v37
	v_mul_f32_e32 v130, v122, v38
	v_mul_f32_e32 v131, v123, v39
	global_store_dwordx4 v2, v[128:131], s[22:23] offset:1024 nt
	v_lshlrev_b32_e32 v120, 16, v68
	v_and_b32_e32 v121, 0xffff0000, v68
	v_lshlrev_b32_e32 v122, 16, v69
	v_and_b32_e32 v123, 0xffff0000, v69
	v_mul_f32_e32 v120, s26, v120
	v_mul_f32_e32 v121, s26, v121
	v_mul_f32_e32 v122, s26, v122
	v_mul_f32_e32 v123, s26, v123
	v_mul_f32_e32 v132, v120, v40
	v_mul_f32_e32 v133, v121, v41
	v_mul_f32_e32 v134, v122, v42
	v_mul_f32_e32 v135, v123, v43
	global_store_dwordx4 v2, v[132:135], s[22:23] offset:2048 nt
	v_lshlrev_b32_e32 v120, 16, v70
	v_and_b32_e32 v121, 0xffff0000, v70
	v_lshlrev_b32_e32 v122, 16, v71
	v_and_b32_e32 v123, 0xffff0000, v71
	v_mul_f32_e32 v120, s26, v120
	v_mul_f32_e32 v121, s26, v121
	v_mul_f32_e32 v122, s26, v122
	v_mul_f32_e32 v123, s26, v123
	v_mul_f32_e32 v136, v120, v44
	v_mul_f32_e32 v137, v121, v45
	v_mul_f32_e32 v138, v122, v46
	v_mul_f32_e32 v139, v123, v47
	global_store_dwordx4 v2, v[136:139], s[22:23] offset:3072 nt
	s_add_u32 s22, s22, s25
	s_addc_u32 s23, s23, 0
	v_readlane_b32 s26, v16, 11
	v_lshlrev_b32_e32 v120, 16, v72
	v_and_b32_e32 v121, 0xffff0000, v72
	v_lshlrev_b32_e32 v122, 16, v73
	v_and_b32_e32 v123, 0xffff0000, v73
	v_mul_f32_e32 v120, s26, v120
	v_mul_f32_e32 v121, s26, v121
	v_mul_f32_e32 v122, s26, v122
	v_mul_f32_e32 v123, s26, v123
	v_mul_f32_e32 v124, v120, v32
	v_mul_f32_e32 v125, v121, v33
	v_mul_f32_e32 v126, v122, v34
	v_mul_f32_e32 v127, v123, v35
	global_store_dwordx4 v2, v[124:127], s[22:23] nt
	v_lshlrev_b32_e32 v120, 16, v74
	v_and_b32_e32 v121, 0xffff0000, v74
	v_lshlrev_b32_e32 v122, 16, v75
	v_and_b32_e32 v123, 0xffff0000, v75
	v_mul_f32_e32 v120, s26, v120
	v_mul_f32_e32 v121, s26, v121
	v_mul_f32_e32 v122, s26, v122
	v_mul_f32_e32 v123, s26, v123
	v_mul_f32_e32 v128, v120, v36
	v_mul_f32_e32 v129, v121, v37
	v_mul_f32_e32 v130, v122, v38
	v_mul_f32_e32 v131, v123, v39
	global_store_dwordx4 v2, v[128:131], s[22:23] offset:1024 nt
	v_lshlrev_b32_e32 v120, 16, v76
	v_and_b32_e32 v121, 0xffff0000, v76
	v_lshlrev_b32_e32 v122, 16, v77
	v_and_b32_e32 v123, 0xffff0000, v77
	v_mul_f32_e32 v120, s26, v120
	v_mul_f32_e32 v121, s26, v121
	v_mul_f32_e32 v122, s26, v122
	v_mul_f32_e32 v123, s26, v123
	v_mul_f32_e32 v132, v120, v40
	v_mul_f32_e32 v133, v121, v41
	v_mul_f32_e32 v134, v122, v42
	v_mul_f32_e32 v135, v123, v43
	global_store_dwordx4 v2, v[132:135], s[22:23] offset:2048 nt
	v_lshlrev_b32_e32 v120, 16, v78
	v_and_b32_e32 v121, 0xffff0000, v78
	v_lshlrev_b32_e32 v122, 16, v79
	v_and_b32_e32 v123, 0xffff0000, v79
	v_mul_f32_e32 v120, s26, v120
	v_mul_f32_e32 v121, s26, v121
	v_mul_f32_e32 v122, s26, v122
	v_mul_f32_e32 v123, s26, v123
	v_mul_f32_e32 v136, v120, v44
	v_mul_f32_e32 v137, v121, v45
	v_mul_f32_e32 v138, v122, v46
	v_mul_f32_e32 v139, v123, v47
	global_store_dwordx4 v2, v[136:139], s[22:23] offset:3072 nt
	s_add_u32 s22, s22, s25
	s_addc_u32 s23, s23, 0
	global_load_dwordx2 v[48:49], v3, s[20:21] nt
	global_load_dwordx2 v[50:51], v3, s[20:21] offset:512 nt
	global_load_dwordx2 v[52:53], v3, s[20:21] offset:1024 nt
	global_load_dwordx2 v[54:55], v3, s[20:21] offset:1536 nt
	s_add_u32 s20, s20, s24
	s_addc_u32 s21, s21, 0
	global_load_dwordx2 v[56:57], v3, s[20:21] nt
	global_load_dwordx2 v[58:59], v3, s[20:21] offset:512 nt
	global_load_dwordx2 v[60:61], v3, s[20:21] offset:1024 nt
	global_load_dwordx2 v[62:63], v3, s[20:21] offset:1536 nt
	s_add_u32 s20, s20, s24
	s_addc_u32 s21, s21, 0
	global_load_dwordx2 v[64:65], v3, s[20:21] nt
	global_load_dwordx2 v[66:67], v3, s[20:21] offset:512 nt
	global_load_dwordx2 v[68:69], v3, s[20:21] offset:1024 nt
	global_load_dwordx2 v[70:71], v3, s[20:21] offset:1536 nt
	s_add_u32 s20, s20, s24
	s_addc_u32 s21, s21, 0
	global_load_dwordx2 v[72:73], v3, s[20:21] nt
	global_load_dwordx2 v[74:75], v3, s[20:21] offset:512 nt
	global_load_dwordx2 v[76:77], v3, s[20:21] offset:1024 nt
	global_load_dwordx2 v[78:79], v3, s[20:21] offset:1536 nt
	s_add_u32 s20, s20, s24
	s_addc_u32 s21, s21, 0
	s_waitcnt vmcnt(32)
; __device__ __forceinline__ float bflo(unsigned w) { return __uint_as_float(w << 16); }
; __device__ __forceinline__ float bfhi(unsigned w) { return __uint_as_float(w & 0xffff0000u); }
; __global__ void __launch_bounds__(512, 2) fwd_megakernel(Args a) {
;     ...
;       for (int m = gw0; m < flim; m += fstep) { f32x4* orow = (f32x4*)(hres + (size_t)m * D) + ln;
;         v2u w[4]; const float rs = nrs;
; #pragma unroll
;         for (int j = 0; j < 4; ++j) w[j] = nw[j];
;         { const int mn = m + fstep; if (mn < flim) { const v2u* xr = (const v2u*)(HB + (size_t)mn * D) + ln; nrs = pg8::row_rstd(slots, mn);
; #pragma unroll
;             for (int j = 0; j < 4; ++j) nw[j] = __builtin_nontemporal_load(xr + 64 * j); } }
; #pragma unroll
;         for (int j = 0; j < 4; ++j) { const f32x4 gg = *((const f32x4*)fg + ln + 64 * j);
;             __builtin_nontemporal_store((f32x4){bflo(w[j].x), bfhi(w[j].x), bflo(w[j].y), bfhi(w[j].y)} * rs * gg, orow + 64 * j); } } }
	v_readlane_b32 s26, v16, 12
	v_lshlrev_b32_e32 v120, 16, v80
	v_and_b32_e32 v121, 0xffff0000, v80
	v_lshlrev_b32_e32 v122, 16, v81
	v_and_b32_e32 v123, 0xffff0000, v81
	v_mul_f32_e32 v120, s26, v120
	v_mul_f32_e32 v121, s26, v121
	v_mul_f32_e32 v122, s26, v122
	v_mul_f32_e32 v123, s26, v123
	v_mul_f32_e32 v124, v120, v32
	v_mul_f32_e32 v125, v121, v33
	v_mul_f32_e32 v126, v122, v34
	v_mul_f32_e32 v127, v123, v35
	global_store_dwordx4 v2, v[124:127], s[22:23] nt
	v_lshlrev_b32_e32 v120, 16, v82
	v_and_b32_e32 v121, 0xffff0000, v82
	v_lshlrev_b32_e32 v122, 16, v83
	v_and_b32_e32 v123, 0xffff0000, v83
	v_mul_f32_e32 v120, s26, v120
	v_mul_f32_e32 v121, s26, v121
	v_mul_f32_e32 v122, s26, v122
	v_mul_f32_e32 v123, s26, v123
	v_mul_f32_e32 v128, v120, v36
	v_mul_f32_e32 v129, v121, v37
	v_mul_f32_e32 v130, v122, v38
	v_mul_f32_e32 v131, v123, v39
	global_store_dwordx4 v2, v[128:131], s[22:23] offset:1024 nt
	v_lshlrev_b32_e32 v120, 16, v84
	v_and_b32_e32 v121, 0xffff0000, v84
	v_lshlrev_b32_e32 v122, 16, v85
	v_and_b32_e32 v123, 0xffff0000, v85
	v_mul_f32_e32 v120, s26, v120
	v_mul_f32_e32 v121, s26, v121
	v_mul_f32_e32 v122, s26, v122
	v_mul_f32_e32 v123, s26, v123
	v_mul_f32_e32 v132, v120, v40
	v_mul_f32_e32 v133, v121, v41
	v_mul_f32_e32 v134, v122, v42
	v_mul_f32_e32 v135, v123, v43
	global_store_dwordx4 v2, v[132:135], s[22:23] offset:2048 nt
	v_lshlrev_b32_e32 v120, 16, v86
	v_and_b32_e32 v121, 0xffff0000, v86
	v_lshlrev_b32_e32 v122, 16, v87
	v_and_b32_e32 v123, 0xffff0000, v87
	v_mul_f32_e32 v120, s26, v120
	v_mul_f32_e32 v121, s26, v121
	v_mul_f32_e32 v122, s26, v122
	v_mul_f32_e32 v123, s26, v123
	v_mul_f32_e32 v136, v120, v44
	v_mul_f32_e32 v137, v121, v45
	v_mul_f32_e32 v138, v122, v46
	v_mul_f32_e32 v139, v123, v47
	global_store_dwordx4 v2, v[136:139], s[22:23] offset:3072 nt
	s_add_u32 s22, s22, s25
	s_addc_u32 s23, s23, 0
	v_readlane_b32 s26, v16, 13
	v_lshlrev_b32_e32 v120, 16, v88
	v_and_b32_e32 v121, 0xffff0000, v88
	v_lshlrev_b32_e32 v122, 16, v89
	v_and_b32_e32 v123, 0xffff0000, v89
	v_mul_f32_e32 v120, s26, v120
	v_mul_f32_e32 v121, s26, v121
	v_mul_f32_e32 v122, s26, v122
	v_mul_f32_e32 v123, s26, v123
	v_mul_f32_e32 v124, v120, v32
	v_mul_f32_e32 v125, v121, v33
	v_mul_f32_e32 v126, v122, v34
	v_mul_f32_e32 v127, v123, v35
	global_store_dwordx4 v2, v[124:127], s[22:23] nt
	v_lshlrev_b32_e32 v120, 16, v90
	v_and_b32_e32 v121, 0xffff0000, v90
	v_lshlrev_b32_e32 v122, 16, v91
	v_and_b32_e32 v123, 0xffff0000, v91
	v_mul_f32_e32 v120, s26, v120
	v_mul_f32_e32 v121, s26, v121
	v_mul_f32_e32 v122, s26, v122
	v_mul_f32_e32 v123, s26, v123
	v_mul_f32_e32 v128, v120, v36
	v_mul_f32_e32 v129, v121, v37
	v_mul_f32_e32 v130, v122, v38
	v_mul_f32_e32 v131, v123, v39
	global_store_dwordx4 v2, v[128:131], s[22:23] offset:1024 nt
	v_lshlrev_b32_e32 v120, 16, v92
	v_and_b32_e32 v121, 0xffff0000, v92
	v_lshlrev_b32_e32 v122, 16, v93
	v_and_b32_e32 v123, 0xffff0000, v93
	v_mul_f32_e32 v120, s26, v120
	v_mul_f32_e32 v121, s26, v121
	v_mul_f32_e32 v122, s26, v122
	v_mul_f32_e32 v123, s26, v123
	v_mul_f32_e32 v132, v120, v40
	v_mul_f32_e32 v133, v121, v41
	v_mul_f32_e32 v134, v122, v42
	v_mul_f32_e32 v135, v123, v43
	global_store_dwordx4 v2, v[132:135], s[22:23] offset:2048 nt
	v_lshlrev_b32_e32 v120, 16, v94
	v_and_b32_e32 v121, 0xffff0000, v94
	v_lshlrev_b32_e32 v122, 16, v95
	v_and_b32_e32 v123, 0xffff0000, v95
	v_mul_f32_e32 v120, s26, v120
	v_mul_f32_e32 v121, s26, v121
	v_mul_f32_e32 v122, s26, v122
	v_mul_f32_e32 v123, s26, v123
	v_mul_f32_e32 v136, v120, v44
	v_mul_f32_e32 v137, v121, v45
	v_mul_f32_e32 v138, v122, v46
	v_mul_f32_e32 v139, v123, v47
	global_store_dwordx4 v2, v[136:139], s[22:23] offset:3072 nt
	s_add_u32 s22, s22, s25
	s_addc_u32 s23, s23, 0
	v_readlane_b32 s26, v16, 14
	v_lshlrev_b32_e32 v120, 16, v96
	v_and_b32_e32 v121, 0xffff0000, v96
	v_lshlrev_b32_e32 v122, 16, v97
	v_and_b32_e32 v123, 0xffff0000, v97
	v_mul_f32_e32 v120, s26, v120
	v_mul_f32_e32 v121, s26, v121
	v_mul_f32_e32 v122, s26, v122
	v_mul_f32_e32 v123, s26, v123
	v_mul_f32_e32 v124, v120, v32
	v_mul_f32_e32 v125, v121, v33
	v_mul_f32_e32 v126, v122, v34
	v_mul_f32_e32 v127, v123, v35
	global_store_dwordx4 v2, v[124:127], s[22:23] nt
	v_lshlrev_b32_e32 v120, 16, v98
	v_and_b32_e32 v121, 0xffff0000, v98
	v_lshlrev_b32_e32 v122, 16, v99
	v_and_b32_e32 v123, 0xffff0000, v99
	v_mul_f32_e32 v120, s26, v120
	v_mul_f32_e32 v121, s26, v121
	v_mul_f32_e32 v122, s26, v122
	v_mul_f32_e32 v123, s26, v123
	v_mul_f32_e32 v128, v120, v36
	v_mul_f32_e32 v129, v121, v37
	v_mul_f32_e32 v130, v122, v38
	v_mul_f32_e32 v131, v123, v39
	global_store_dwordx4 v2, v[128:131], s[22:23] offset:1024 nt
	v_lshlrev_b32_e32 v120, 16, v100
	v_and_b32_e32 v121, 0xffff0000, v100
	v_lshlrev_b32_e32 v122, 16, v101
	v_and_b32_e32 v123, 0xffff0000, v101
	v_mul_f32_e32 v120, s26, v120
	v_mul_f32_e32 v121, s26, v121
	v_mul_f32_e32 v122, s26, v122
	v_mul_f32_e32 v123, s26, v123
	v_mul_f32_e32 v132, v120, v40
	v_mul_f32_e32 v133, v121, v41
	v_mul_f32_e32 v134, v122, v42
	v_mul_f32_e32 v135, v123, v43
	global_store_dwordx4 v2, v[132:135], s[22:23] offset:2048 nt
	v_lshlrev_b32_e32 v120, 16, v102
	v_and_b32_e32 v121, 0xffff0000, v102
	v_lshlrev_b32_e32 v122, 16, v103
	v_and_b32_e32 v123, 0xffff0000, v103
	v_mul_f32_e32 v120, s26, v120
	v_mul_f32_e32 v121, s26, v121
	v_mul_f32_e32 v122, s26, v122
	v_mul_f32_e32 v123, s26, v123
	v_mul_f32_e32 v136, v120, v44
	v_mul_f32_e32 v137, v121, v45
	v_mul_f32_e32 v138, v122, v46
	v_mul_f32_e32 v139, v123, v47
	global_store_dwordx4 v2, v[136:139], s[22:23] offset:3072 nt
	s_add_u32 s22, s22, s25
	s_addc_u32 s23, s23, 0
	v_readlane_b32 s26, v16, 15
; __device__ __forceinline__ float bflo(unsigned w) { return __uint_as_float(w << 16); }
; __device__ __forceinline__ float bfhi(unsigned w) { return __uint_as_float(w & 0xffff0000u); }
; __global__ void __launch_bounds__(512, 2) fwd_megakernel(Args a) {
;     ...
;       for (int m = gw0; m < flim; m += fstep) { f32x4* orow = (f32x4*)(hres + (size_t)m * D) + ln;
;         v2u w[4]; const float rs = nrs;
; #pragma unroll
;         for (int j = 0; j < 4; ++j) w[j] = nw[j];
;         { const int mn = m + fstep; if (mn < flim) { const v2u* xr = (const v2u*)(HB + (size_t)mn * D) + ln; nrs = pg8::row_rstd(slots, mn);
; #pragma unroll
;             for (int j = 0; j < 4; ++j) nw[j] = __builtin_nontemporal_load(xr + 64 * j); } }
; #pragma unroll
;         for (int j = 0; j < 4; ++j) { const f32x4 gg = *((const f32x4*)fg + ln + 64 * j);
;             __builtin_nontemporal_store((f32x4){bflo(w[j].x), bfhi(w[j].x), bflo(w[j].y), bfhi(w[j].y)} * rs * gg, orow + 64 * j); } } }
	v_lshlrev_b32_e32 v120, 16, v104
	v_and_b32_e32 v121, 0xffff0000, v104
	v_lshlrev_b32_e32 v122, 16, v105
	v_and_b32_e32 v123, 0xffff0000, v105
	v_mul_f32_e32 v120, s26, v120
	v_mul_f32_e32 v121, s26, v121
	v_mul_f32_e32 v122, s26, v122
	v_mul_f32_e32 v123, s26, v123
	v_mul_f32_e32 v124, v120, v32
	v_mul_f32_e32 v125, v121, v33
	v_mul_f32_e32 v126, v122, v34
	v_mul_f32_e32 v127, v123, v35
	global_store_dwordx4 v2, v[124:127], s[22:23] nt
	v_lshlrev_b32_e32 v120, 16, v106
	v_and_b32_e32 v121, 0xffff0000, v106
	v_lshlrev_b32_e32 v122, 16, v107
	v_and_b32_e32 v123, 0xffff0000, v107
	v_mul_f32_e32 v120, s26, v120
	v_mul_f32_e32 v121, s26, v121
	v_mul_f32_e32 v122, s26, v122
	v_mul_f32_e32 v123, s26, v123
	v_mul_f32_e32 v128, v120, v36
	v_mul_f32_e32 v129, v121, v37
	v_mul_f32_e32 v130, v122, v38
	v_mul_f32_e32 v131, v123, v39
	global_store_dwordx4 v2, v[128:131], s[22:23] offset:1024 nt
	v_lshlrev_b32_e32 v120, 16, v108
	v_and_b32_e32 v121, 0xffff0000, v108
	v_lshlrev_b32_e32 v122, 16, v109
	v_and_b32_e32 v123, 0xffff0000, v109
	v_mul_f32_e32 v120, s26, v120
	v_mul_f32_e32 v121, s26, v121
	v_mul_f32_e32 v122, s26, v122
	v_mul_f32_e32 v123, s26, v123
	v_mul_f32_e32 v132, v120, v40
	v_mul_f32_e32 v133, v121, v41
	v_mul_f32_e32 v134, v122, v42
	v_mul_f32_e32 v135, v123, v43
	global_store_dwordx4 v2, v[132:135], s[22:23] offset:2048 nt
	v_lshlrev_b32_e32 v120, 16, v110
	v_and_b32_e32 v121, 0xffff0000, v110
	v_lshlrev_b32_e32 v122, 16, v111
	v_and_b32_e32 v123, 0xffff0000, v111
	v_mul_f32_e32 v120, s26, v120
	v_mul_f32_e32 v121, s26, v121
	v_mul_f32_e32 v122, s26, v122
	v_mul_f32_e32 v123, s26, v123
	v_mul_f32_e32 v136, v120, v44
	v_mul_f32_e32 v137, v121, v45
	v_mul_f32_e32 v138, v122, v46
	v_mul_f32_e32 v139, v123, v47
	global_store_dwordx4 v2, v[136:139], s[22:23] offset:3072 nt
	s_add_u32 s22, s22, s25
	s_addc_u32 s23, s23, 0
	global_load_dwordx2 v[80:81], v3, s[20:21] nt
	global_load_dwordx2 v[82:83], v3, s[20:21] offset:512 nt
	global_load_dwordx2 v[84:85], v3, s[20:21] offset:1024 nt
	global_load_dwordx2 v[86:87], v3, s[20:21] offset:1536 nt
	s_add_u32 s20, s20, s24
	s_addc_u32 s21, s21, 0
	global_load_dwordx2 v[88:89], v3, s[20:21] nt
	global_load_dwordx2 v[90:91], v3, s[20:21] offset:512 nt
	global_load_dwordx2 v[92:93], v3, s[20:21] offset:1024 nt
	global_load_dwordx2 v[94:95], v3, s[20:21] offset:1536 nt
	s_add_u32 s20, s20, s24
	s_addc_u32 s21, s21, 0
	global_load_dwordx2 v[96:97], v3, s[20:21] nt
	global_load_dwordx2 v[98:99], v3, s[20:21] offset:512 nt
	global_load_dwordx2 v[100:101], v3, s[20:21] offset:1024 nt
	global_load_dwordx2 v[102:103], v3, s[20:21] offset:1536 nt
	s_add_u32 s20, s20, s24
	s_addc_u32 s21, s21, 0
	global_load_dwordx2 v[104:105], v3, s[20:21] nt
	global_load_dwordx2 v[106:107], v3, s[20:21] offset:512 nt
	global_load_dwordx2 v[108:109], v3, s[20:21] offset:1024 nt
	global_load_dwordx2 v[110:111], v3, s[20:21] offset:1536 nt
	s_add_u32 s20, s20, s24
	s_addc_u32 s21, s21, 0
	s_waitcnt vmcnt(32)
	v_readlane_b32 s26, v16, 16
	v_lshlrev_b32_e32 v120, 16, v48
	v_and_b32_e32 v121, 0xffff0000, v48
	v_lshlrev_b32_e32 v122, 16, v49
	v_and_b32_e32 v123, 0xffff0000, v49
	v_mul_f32_e32 v120, s26, v120
	v_mul_f32_e32 v121, s26, v121
	v_mul_f32_e32 v122, s26, v122
	v_mul_f32_e32 v123, s26, v123
	v_mul_f32_e32 v124, v120, v32
	v_mul_f32_e32 v125, v121, v33
	v_mul_f32_e32 v126, v122, v34
	v_mul_f32_e32 v127, v123, v35
	global_store_dwordx4 v2, v[124:127], s[22:23] nt
	v_lshlrev_b32_e32 v120, 16, v50
	v_and_b32_e32 v121, 0xffff0000, v50
	v_lshlrev_b32_e32 v122, 16, v51
	v_and_b32_e32 v123, 0xffff0000, v51
	v_mul_f32_e32 v120, s26, v120
	v_mul_f32_e32 v121, s26, v121
	v_mul_f32_e32 v122, s26, v122
	v_mul_f32_e32 v123, s26, v123
	v_mul_f32_e32 v128, v120, v36
	v_mul_f32_e32 v129, v121, v37
	v_mul_f32_e32 v130, v122, v38
	v_mul_f32_e32 v131, v123, v39
	global_store_dwordx4 v2, v[128:131], s[22:23] offset:1024 nt
	v_lshlrev_b32_e32 v120, 16, v52
	v_and_b32_e32 v121, 0xffff0000, v52
	v_lshlrev_b32_e32 v122, 16, v53
	v_and_b32_e32 v123, 0xffff0000, v53
	v_mul_f32_e32 v120, s26, v120
	v_mul_f32_e32 v121, s26, v121
	v_mul_f32_e32 v122, s26, v122
	v_mul_f32_e32 v123, s26, v123
	v_mul_f32_e32 v132, v120, v40
	v_mul_f32_e32 v133, v121, v41
	v_mul_f32_e32 v134, v122, v42
	v_mul_f32_e32 v135, v123, v43
	global_store_dwordx4 v2, v[132:135], s[22:23] offset:2048 nt
	v_lshlrev_b32_e32 v120, 16, v54
	v_and_b32_e32 v121, 0xffff0000, v54
	v_lshlrev_b32_e32 v122, 16, v55
	v_and_b32_e32 v123, 0xffff0000, v55
	v_mul_f32_e32 v120, s26, v120
	v_mul_f32_e32 v121, s26, v121
	v_mul_f32_e32 v122, s26, v122
	v_mul_f32_e32 v123, s26, v123
	v_mul_f32_e32 v136, v120, v44
	v_mul_f32_e32 v137, v121, v45
	v_mul_f32_e32 v138, v122, v46
	v_mul_f32_e32 v139, v123, v47
	global_store_dwordx4 v2, v[136:139], s[22:23] offset:3072 nt
	s_add_u32 s22, s22, s25
	s_addc_u32 s23, s23, 0
	v_readlane_b32 s26, v16, 17
	v_lshlrev_b32_e32 v120, 16, v56
	v_and_b32_e32 v121, 0xffff0000, v56
	v_lshlrev_b32_e32 v122, 16, v57
	v_and_b32_e32 v123, 0xffff0000, v57
	v_mul_f32_e32 v120, s26, v120
	v_mul_f32_e32 v121, s26, v121
	v_mul_f32_e32 v122, s26, v122
	v_mul_f32_e32 v123, s26, v123
	v_mul_f32_e32 v124, v120, v32
	v_mul_f32_e32 v125, v121, v33
	v_mul_f32_e32 v126, v122, v34
	v_mul_f32_e32 v127, v123, v35
	global_store_dwordx4 v2, v[124:127], s[22:23] nt
	v_lshlrev_b32_e32 v120, 16, v58
	v_and_b32_e32 v121, 0xffff0000, v58
	v_lshlrev_b32_e32 v122, 16, v59
	v_and_b32_e32 v123, 0xffff0000, v59
	v_mul_f32_e32 v120, s26, v120
	v_mul_f32_e32 v121, s26, v121
	v_mul_f32_e32 v122, s26, v122
	v_mul_f32_e32 v123, s26, v123
	v_mul_f32_e32 v128, v120, v36
	v_mul_f32_e32 v129, v121, v37
; __device__ __forceinline__ float bflo(unsigned w) { return __uint_as_float(w << 16); }
; __device__ __forceinline__ float bfhi(unsigned w) { return __uint_as_float(w & 0xffff0000u); }
; __global__ void __launch_bounds__(512, 2) fwd_megakernel(Args a) {
;     ...
;       for (int m = gw0; m < flim; m += fstep) { f32x4* orow = (f32x4*)(hres + (size_t)m * D) + ln;
;         v2u w[4]; const float rs = nrs;
; #pragma unroll
;         for (int j = 0; j < 4; ++j) w[j] = nw[j];
;         { const int mn = m + fstep; if (mn < flim) { const v2u* xr = (const v2u*)(HB + (size_t)mn * D) + ln; nrs = pg8::row_rstd(slots, mn);
; #pragma unroll
;             for (int j = 0; j < 4; ++j) nw[j] = __builtin_nontemporal_load(xr + 64 * j); } }
; #pragma unroll
;         for (int j = 0; j < 4; ++j) { const f32x4 gg = *((const f32x4*)fg + ln + 64 * j);
;             __builtin_nontemporal_store((f32x4){bflo(w[j].x), bfhi(w[j].x), bflo(w[j].y), bfhi(w[j].y)} * rs * gg, orow + 64 * j); } } }
	v_mul_f32_e32 v130, v122, v38
	v_mul_f32_e32 v131, v123, v39
	global_store_dwordx4 v2, v[128:131], s[22:23] offset:1024 nt
	v_lshlrev_b32_e32 v120, 16, v60
	v_and_b32_e32 v121, 0xffff0000, v60
	v_lshlrev_b32_e32 v122, 16, v61
	v_and_b32_e32 v123, 0xffff0000, v61
	v_mul_f32_e32 v120, s26, v120
	v_mul_f32_e32 v121, s26, v121
	v_mul_f32_e32 v122, s26, v122
	v_mul_f32_e32 v123, s26, v123
	v_mul_f32_e32 v132, v120, v40
	v_mul_f32_e32 v133, v121, v41
	v_mul_f32_e32 v134, v122, v42
	v_mul_f32_e32 v135, v123, v43
	global_store_dwordx4 v2, v[132:135], s[22:23] offset:2048 nt
	v_lshlrev_b32_e32 v120, 16, v62
	v_and_b32_e32 v121, 0xffff0000, v62
	v_lshlrev_b32_e32 v122, 16, v63
	v_and_b32_e32 v123, 0xffff0000, v63
	v_mul_f32_e32 v120, s26, v120
	v_mul_f32_e32 v121, s26, v121
	v_mul_f32_e32 v122, s26, v122
	v_mul_f32_e32 v123, s26, v123
	v_mul_f32_e32 v136, v120, v44
	v_mul_f32_e32 v137, v121, v45
	v_mul_f32_e32 v138, v122, v46
	v_mul_f32_e32 v139, v123, v47
	global_store_dwordx4 v2, v[136:139], s[22:23] offset:3072 nt
	s_add_u32 s22, s22, s25
	s_addc_u32 s23, s23, 0
	v_readlane_b32 s26, v16, 18
	v_lshlrev_b32_e32 v120, 16, v64
	v_and_b32_e32 v121, 0xffff0000, v64
	v_lshlrev_b32_e32 v122, 16, v65
	v_and_b32_e32 v123, 0xffff0000, v65
	v_mul_f32_e32 v120, s26, v120
	v_mul_f32_e32 v121, s26, v121
	v_mul_f32_e32 v122, s26, v122
	v_mul_f32_e32 v123, s26, v123
	v_mul_f32_e32 v124, v120, v32
	v_mul_f32_e32 v125, v121, v33
	v_mul_f32_e32 v126, v122, v34
	v_mul_f32_e32 v127, v123, v35
	global_store_dwordx4 v2, v[124:127], s[22:23] nt
	v_lshlrev_b32_e32 v120, 16, v66
	v_and_b32_e32 v121, 0xffff0000, v66
	v_lshlrev_b32_e32 v122, 16, v67
	v_and_b32_e32 v123, 0xffff0000, v67
	v_mul_f32_e32 v120, s26, v120
	v_mul_f32_e32 v121, s26, v121
	v_mul_f32_e32 v122, s26, v122
	v_mul_f32_e32 v123, s26, v123
	v_mul_f32_e32 v128, v120, v36
	v_mul_f32_e32 v129, v121, v37
	v_mul_f32_e32 v130, v122, v38
	v_mul_f32_e32 v131, v123, v39
	global_store_dwordx4 v2, v[128:131], s[22:23] offset:1024 nt
	v_lshlrev_b32_e32 v120, 16, v68
	v_and_b32_e32 v121, 0xffff0000, v68
	v_lshlrev_b32_e32 v122, 16, v69
	v_and_b32_e32 v123, 0xffff0000, v69
	v_mul_f32_e32 v120, s26, v120
	v_mul_f32_e32 v121, s26, v121
	v_mul_f32_e32 v122, s26, v122
	v_mul_f32_e32 v123, s26, v123
	v_mul_f32_e32 v132, v120, v40
	v_mul_f32_e32 v133, v121, v41
	v_mul_f32_e32 v134, v122, v42
	v_mul_f32_e32 v135, v123, v43
	global_store_dwordx4 v2, v[132:135], s[22:23] offset:2048 nt
	v_lshlrev_b32_e32 v120, 16, v70
	v_and_b32_e32 v121, 0xffff0000, v70
	v_lshlrev_b32_e32 v122, 16, v71
	v_and_b32_e32 v123, 0xffff0000, v71
	v_mul_f32_e32 v120, s26, v120
	v_mul_f32_e32 v121, s26, v121
	v_mul_f32_e32 v122, s26, v122
	v_mul_f32_e32 v123, s26, v123
	v_mul_f32_e32 v136, v120, v44
	v_mul_f32_e32 v137, v121, v45
	v_mul_f32_e32 v138, v122, v46
	v_mul_f32_e32 v139, v123, v47
	global_store_dwordx4 v2, v[136:139], s[22:23] offset:3072 nt
	s_add_u32 s22, s22, s25
	s_addc_u32 s23, s23, 0
	v_readlane_b32 s26, v16, 19
	v_lshlrev_b32_e32 v120, 16, v72
	v_and_b32_e32 v121, 0xffff0000, v72
	v_lshlrev_b32_e32 v122, 16, v73
	v_and_b32_e32 v123, 0xffff0000, v73
	v_mul_f32_e32 v120, s26, v120
	v_mul_f32_e32 v121, s26, v121
	v_mul_f32_e32 v122, s26, v122
	v_mul_f32_e32 v123, s26, v123
	v_mul_f32_e32 v124, v120, v32
	v_mul_f32_e32 v125, v121, v33
	v_mul_f32_e32 v126, v122, v34
	v_mul_f32_e32 v127, v123, v35
	global_store_dwordx4 v2, v[124:127], s[22:23] nt
	v_lshlrev_b32_e32 v120, 16, v74
	v_and_b32_e32 v121, 0xffff0000, v74
	v_lshlrev_b32_e32 v122, 16, v75
	v_and_b32_e32 v123, 0xffff0000, v75
	v_mul_f32_e32 v120, s26, v120
	v_mul_f32_e32 v121, s26, v121
	v_mul_f32_e32 v122, s26, v122
	v_mul_f32_e32 v123, s26, v123
	v_mul_f32_e32 v128, v120, v36
	v_mul_f32_e32 v129, v121, v37
	v_mul_f32_e32 v130, v122, v38
	v_mul_f32_e32 v131, v123, v39
	global_store_dwordx4 v2, v[128:131], s[22:23] offset:1024 nt
	v_lshlrev_b32_e32 v120, 16, v76
	v_and_b32_e32 v121, 0xffff0000, v76
	v_lshlrev_b32_e32 v122, 16, v77
	v_and_b32_e32 v123, 0xffff0000, v77
	v_mul_f32_e32 v120, s26, v120
	v_mul_f32_e32 v121, s26, v121
	v_mul_f32_e32 v122, s26, v122
	v_mul_f32_e32 v123, s26, v123
	v_mul_f32_e32 v132, v120, v40
	v_mul_f32_e32 v133, v121, v41
	v_mul_f32_e32 v134, v122, v42
	v_mul_f32_e32 v135, v123, v43
	global_store_dwordx4 v2, v[132:135], s[22:23] offset:2048 nt
	v_lshlrev_b32_e32 v120, 16, v78
	v_and_b32_e32 v121, 0xffff0000, v78
	v_lshlrev_b32_e32 v122, 16, v79
	v_and_b32_e32 v123, 0xffff0000, v79
	v_mul_f32_e32 v120, s26, v120
	v_mul_f32_e32 v121, s26, v121
	v_mul_f32_e32 v122, s26, v122
	v_mul_f32_e32 v123, s26, v123
	v_mul_f32_e32 v136, v120, v44
	v_mul_f32_e32 v137, v121, v45
	v_mul_f32_e32 v138, v122, v46
	v_mul_f32_e32 v139, v123, v47
	global_store_dwordx4 v2, v[136:139], s[22:23] offset:3072 nt
	s_add_u32 s22, s22, s25
	s_addc_u32 s23, s23, 0
	global_load_dwordx2 v[48:49], v3, s[20:21] nt
	global_load_dwordx2 v[50:51], v3, s[20:21] offset:512 nt
	global_load_dwordx2 v[52:53], v3, s[20:21] offset:1024 nt
	global_load_dwordx2 v[54:55], v3, s[20:21] offset:1536 nt
	s_add_u32 s20, s20, s24
	s_addc_u32 s21, s21, 0
	global_load_dwordx2 v[56:57], v3, s[20:21] nt
	global_load_dwordx2 v[58:59], v3, s[20:21] offset:512 nt
	global_load_dwordx2 v[60:61], v3, s[20:21] offset:1024 nt
	global_load_dwordx2 v[62:63], v3, s[20:21] offset:1536 nt
	s_add_u32 s20, s20, s24
	s_addc_u32 s21, s21, 0
	global_load_dwordx2 v[64:65], v3, s[20:21] nt
	global_load_dwordx2 v[66:67], v3, s[20:21] offset:512 nt
	global_load_dwordx2 v[68:69], v3, s[20:21] offset:1024 nt
	global_load_dwordx2 v[70:71], v3, s[20:21] offset:1536 nt
	s_add_u32 s20, s20, s24
	s_addc_u32 s21, s21, 0
	global_load_dwordx2 v[72:73], v3, s[20:21] nt
	global_load_dwordx2 v[74:75], v3, s[20:21] offset:512 nt
	global_load_dwordx2 v[76:77], v3, s[20:21] offset:1024 nt
	global_load_dwordx2 v[78:79], v3, s[20:21] offset:1536 nt
	s_add_u32 s20, s20, s24
	s_addc_u32 s21, s21, 0
	s_waitcnt vmcnt(32)
; __device__ __forceinline__ float bflo(unsigned w) { return __uint_as_float(w << 16); }
; __device__ __forceinline__ float bfhi(unsigned w) { return __uint_as_float(w & 0xffff0000u); }
; __global__ void __launch_bounds__(512, 2) fwd_megakernel(Args a) {
;     ...
;       for (int m = gw0; m < flim; m += fstep) { f32x4* orow = (f32x4*)(hres + (size_t)m * D) + ln;
;         v2u w[4]; const float rs = nrs;
; #pragma unroll
;         for (int j = 0; j < 4; ++j) w[j] = nw[j];
;         { const int mn = m + fstep; if (mn < flim) { const v2u* xr = (const v2u*)(HB + (size_t)mn * D) + ln; nrs = pg8::row_rstd(slots, mn);
; #pragma unroll
;             for (int j = 0; j < 4; ++j) nw[j] = __builtin_nontemporal_load(xr + 64 * j); } }
; #pragma unroll
;         for (int j = 0; j < 4; ++j) { const f32x4 gg = *((const f32x4*)fg + ln + 64 * j);
;             __builtin_nontemporal_store((f32x4){bflo(w[j].x), bfhi(w[j].x), bflo(w[j].y), bfhi(w[j].y)} * rs * gg, orow + 64 * j); } } }
	v_readlane_b32 s26, v16, 20
	v_lshlrev_b32_e32 v120, 16, v80
	v_and_b32_e32 v121, 0xffff0000, v80
	v_lshlrev_b32_e32 v122, 16, v81
	v_and_b32_e32 v123, 0xffff0000, v81
	v_mul_f32_e32 v120, s26, v120
	v_mul_f32_e32 v121, s26, v121
	v_mul_f32_e32 v122, s26, v122
	v_mul_f32_e32 v123, s26, v123
	v_mul_f32_e32 v124, v120, v32
	v_mul_f32_e32 v125, v121, v33
	v_mul_f32_e32 v126, v122, v34
	v_mul_f32_e32 v127, v123, v35
	global_store_dwordx4 v2, v[124:127], s[22:23] nt
	v_lshlrev_b32_e32 v120, 16, v82
	v_and_b32_e32 v121, 0xffff0000, v82
	v_lshlrev_b32_e32 v122, 16, v83
	v_and_b32_e32 v123, 0xffff0000, v83
	v_mul_f32_e32 v120, s26, v120
	v_mul_f32_e32 v121, s26, v121
	v_mul_f32_e32 v122, s26, v122
	v_mul_f32_e32 v123, s26, v123
	v_mul_f32_e32 v128, v120, v36
	v_mul_f32_e32 v129, v121, v37
	v_mul_f32_e32 v130, v122, v38
	v_mul_f32_e32 v131, v123, v39
	global_store_dwordx4 v2, v[128:131], s[22:23] offset:1024 nt
	v_lshlrev_b32_e32 v120, 16, v84
	v_and_b32_e32 v121, 0xffff0000, v84
	v_lshlrev_b32_e32 v122, 16, v85
	v_and_b32_e32 v123, 0xffff0000, v85
	v_mul_f32_e32 v120, s26, v120
	v_mul_f32_e32 v121, s26, v121
	v_mul_f32_e32 v122, s26, v122
	v_mul_f32_e32 v123, s26, v123
	v_mul_f32_e32 v132, v120, v40
	v_mul_f32_e32 v133, v121, v41
	v_mul_f32_e32 v134, v122, v42
	v_mul_f32_e32 v135, v123, v43
	global_store_dwordx4 v2, v[132:135], s[22:23] offset:2048 nt
	v_lshlrev_b32_e32 v120, 16, v86
	v_and_b32_e32 v121, 0xffff0000, v86
	v_lshlrev_b32_e32 v122, 16, v87
	v_and_b32_e32 v123, 0xffff0000, v87
	v_mul_f32_e32 v120, s26, v120
	v_mul_f32_e32 v121, s26, v121
	v_mul_f32_e32 v122, s26, v122
	v_mul_f32_e32 v123, s26, v123
	v_mul_f32_e32 v136, v120, v44
	v_mul_f32_e32 v137, v121, v45
	v_mul_f32_e32 v138, v122, v46
	v_mul_f32_e32 v139, v123, v47
	global_store_dwordx4 v2, v[136:139], s[22:23] offset:3072 nt
	s_add_u32 s22, s22, s25
	s_addc_u32 s23, s23, 0
	v_readlane_b32 s26, v16, 21
	v_lshlrev_b32_e32 v120, 16, v88
	v_and_b32_e32 v121, 0xffff0000, v88
	v_lshlrev_b32_e32 v122, 16, v89
	v_and_b32_e32 v123, 0xffff0000, v89
	v_mul_f32_e32 v120, s26, v120
	v_mul_f32_e32 v121, s26, v121
	v_mul_f32_e32 v122, s26, v122
	v_mul_f32_e32 v123, s26, v123
	v_mul_f32_e32 v124, v120, v32
	v_mul_f32_e32 v125, v121, v33
	v_mul_f32_e32 v126, v122, v34
	v_mul_f32_e32 v127, v123, v35
	global_store_dwordx4 v2, v[124:127], s[22:23] nt
	v_lshlrev_b32_e32 v120, 16, v90
	v_and_b32_e32 v121, 0xffff0000, v90
	v_lshlrev_b32_e32 v122, 16, v91
	v_and_b32_e32 v123, 0xffff0000, v91
	v_mul_f32_e32 v120, s26, v120
	v_mul_f32_e32 v121, s26, v121
	v_mul_f32_e32 v122, s26, v122
	v_mul_f32_e32 v123, s26, v123
	v_mul_f32_e32 v128, v120, v36
	v_mul_f32_e32 v129, v121, v37
	v_mul_f32_e32 v130, v122, v38
	v_mul_f32_e32 v131, v123, v39
	global_store_dwordx4 v2, v[128:131], s[22:23] offset:1024 nt
	v_lshlrev_b32_e32 v120, 16, v92
	v_and_b32_e32 v121, 0xffff0000, v92
	v_lshlrev_b32_e32 v122, 16, v93
	v_and_b32_e32 v123, 0xffff0000, v93
	v_mul_f32_e32 v120, s26, v120
	v_mul_f32_e32 v121, s26, v121
	v_mul_f32_e32 v122, s26, v122
	v_mul_f32_e32 v123, s26, v123
	v_mul_f32_e32 v132, v120, v40
	v_mul_f32_e32 v133, v121, v41
	v_mul_f32_e32 v134, v122, v42
	v_mul_f32_e32 v135, v123, v43
	global_store_dwordx4 v2, v[132:135], s[22:23] offset:2048 nt
	v_lshlrev_b32_e32 v120, 16, v94
	v_and_b32_e32 v121, 0xffff0000, v94
	v_lshlrev_b32_e32 v122, 16, v95
	v_and_b32_e32 v123, 0xffff0000, v95
	v_mul_f32_e32 v120, s26, v120
	v_mul_f32_e32 v121, s26, v121
	v_mul_f32_e32 v122, s26, v122
	v_mul_f32_e32 v123, s26, v123
	v_mul_f32_e32 v136, v120, v44
	v_mul_f32_e32 v137, v121, v45
	v_mul_f32_e32 v138, v122, v46
	v_mul_f32_e32 v139, v123, v47
	global_store_dwordx4 v2, v[136:139], s[22:23] offset:3072 nt
	s_add_u32 s22, s22, s25
	s_addc_u32 s23, s23, 0
	v_readlane_b32 s26, v16, 22
	v_lshlrev_b32_e32 v120, 16, v96
	v_and_b32_e32 v121, 0xffff0000, v96
	v_lshlrev_b32_e32 v122, 16, v97
	v_and_b32_e32 v123, 0xffff0000, v97
	v_mul_f32_e32 v120, s26, v120
	v_mul_f32_e32 v121, s26, v121
	v_mul_f32_e32 v122, s26, v122
	v_mul_f32_e32 v123, s26, v123
	v_mul_f32_e32 v124, v120, v32
	v_mul_f32_e32 v125, v121, v33
	v_mul_f32_e32 v126, v122, v34
	v_mul_f32_e32 v127, v123, v35
	global_store_dwordx4 v2, v[124:127], s[22:23] nt
	v_lshlrev_b32_e32 v120, 16, v98
	v_and_b32_e32 v121, 0xffff0000, v98
	v_lshlrev_b32_e32 v122, 16, v99
	v_and_b32_e32 v123, 0xffff0000, v99
	v_mul_f32_e32 v120, s26, v120
	v_mul_f32_e32 v121, s26, v121
	v_mul_f32_e32 v122, s26, v122
	v_mul_f32_e32 v123, s26, v123
	v_mul_f32_e32 v128, v120, v36
	v_mul_f32_e32 v129, v121, v37
	v_mul_f32_e32 v130, v122, v38
	v_mul_f32_e32 v131, v123, v39
	global_store_dwordx4 v2, v[128:131], s[22:23] offset:1024 nt
	v_lshlrev_b32_e32 v120, 16, v100
	v_and_b32_e32 v121, 0xffff0000, v100
	v_lshlrev_b32_e32 v122, 16, v101
	v_and_b32_e32 v123, 0xffff0000, v101
	v_mul_f32_e32 v120, s26, v120
	v_mul_f32_e32 v121, s26, v121
	v_mul_f32_e32 v122, s26, v122
	v_mul_f32_e32 v123, s26, v123
	v_mul_f32_e32 v132, v120, v40
	v_mul_f32_e32 v133, v121, v41
	v_mul_f32_e32 v134, v122, v42
	v_mul_f32_e32 v135, v123, v43
	global_store_dwordx4 v2, v[132:135], s[22:23] offset:2048 nt
	v_lshlrev_b32_e32 v120, 16, v102
	v_and_b32_e32 v121, 0xffff0000, v102
	v_lshlrev_b32_e32 v122, 16, v103
	v_and_b32_e32 v123, 0xffff0000, v103
	v_mul_f32_e32 v120, s26, v120
	v_mul_f32_e32 v121, s26, v121
	v_mul_f32_e32 v122, s26, v122
	v_mul_f32_e32 v123, s26, v123
	v_mul_f32_e32 v136, v120, v44
	v_mul_f32_e32 v137, v121, v45
	v_mul_f32_e32 v138, v122, v46
	v_mul_f32_e32 v139, v123, v47
	global_store_dwordx4 v2, v[136:139], s[22:23] offset:3072 nt
	s_add_u32 s22, s22, s25
	s_addc_u32 s23, s23, 0
	v_readlane_b32 s26, v16, 23
; __device__ __forceinline__ float bflo(unsigned w) { return __uint_as_float(w << 16); }
; __device__ __forceinline__ float bfhi(unsigned w) { return __uint_as_float(w & 0xffff0000u); }
; __global__ void __launch_bounds__(512, 2) fwd_megakernel(Args a) {
;     ...
;       for (int m = gw0; m < flim; m += fstep) { f32x4* orow = (f32x4*)(hres + (size_t)m * D) + ln;
;         v2u w[4]; const float rs = nrs;
; #pragma unroll
;         for (int j = 0; j < 4; ++j) w[j] = nw[j];
;         { const int mn = m + fstep; if (mn < flim) { const v2u* xr = (const v2u*)(HB + (size_t)mn * D) + ln; nrs = pg8::row_rstd(slots, mn);
; #pragma unroll
;             for (int j = 0; j < 4; ++j) nw[j] = __builtin_nontemporal_load(xr + 64 * j); } }
; #pragma unroll
;         for (int j = 0; j < 4; ++j) { const f32x4 gg = *((const f32x4*)fg + ln + 64 * j);
;             __builtin_nontemporal_store((f32x4){bflo(w[j].x), bfhi(w[j].x), bflo(w[j].y), bfhi(w[j].y)} * rs * gg, orow + 64 * j); } } }
	v_lshlrev_b32_e32 v120, 16, v104
	v_and_b32_e32 v121, 0xffff0000, v104
	v_lshlrev_b32_e32 v122, 16, v105
	v_and_b32_e32 v123, 0xffff0000, v105
	v_mul_f32_e32 v120, s26, v120
	v_mul_f32_e32 v121, s26, v121
	v_mul_f32_e32 v122, s26, v122
	v_mul_f32_e32 v123, s26, v123
	v_mul_f32_e32 v124, v120, v32
	v_mul_f32_e32 v125, v121, v33
	v_mul_f32_e32 v126, v122, v34
	v_mul_f32_e32 v127, v123, v35
	global_store_dwordx4 v2, v[124:127], s[22:23] nt
	v_lshlrev_b32_e32 v120, 16, v106
	v_and_b32_e32 v121, 0xffff0000, v106
	v_lshlrev_b32_e32 v122, 16, v107
	v_and_b32_e32 v123, 0xffff0000, v107
	v_mul_f32_e32 v120, s26, v120
	v_mul_f32_e32 v121, s26, v121
	v_mul_f32_e32 v122, s26, v122
	v_mul_f32_e32 v123, s26, v123
	v_mul_f32_e32 v128, v120, v36
	v_mul_f32_e32 v129, v121, v37
	v_mul_f32_e32 v130, v122, v38
	v_mul_f32_e32 v131, v123, v39
	global_store_dwordx4 v2, v[128:131], s[22:23] offset:1024 nt
	v_lshlrev_b32_e32 v120, 16, v108
	v_and_b32_e32 v121, 0xffff0000, v108
	v_lshlrev_b32_e32 v122, 16, v109
	v_and_b32_e32 v123, 0xffff0000, v109
	v_mul_f32_e32 v120, s26, v120
	v_mul_f32_e32 v121, s26, v121
	v_mul_f32_e32 v122, s26, v122
	v_mul_f32_e32 v123, s26, v123
	v_mul_f32_e32 v132, v120, v40
	v_mul_f32_e32 v133, v121, v41
	v_mul_f32_e32 v134, v122, v42
	v_mul_f32_e32 v135, v123, v43
	global_store_dwordx4 v2, v[132:135], s[22:23] offset:2048 nt
	v_lshlrev_b32_e32 v120, 16, v110
	v_and_b32_e32 v121, 0xffff0000, v110
	v_lshlrev_b32_e32 v122, 16, v111
	v_and_b32_e32 v123, 0xffff0000, v111
	v_mul_f32_e32 v120, s26, v120
	v_mul_f32_e32 v121, s26, v121
	v_mul_f32_e32 v122, s26, v122
	v_mul_f32_e32 v123, s26, v123
	v_mul_f32_e32 v136, v120, v44
	v_mul_f32_e32 v137, v121, v45
	v_mul_f32_e32 v138, v122, v46
	v_mul_f32_e32 v139, v123, v47
	global_store_dwordx4 v2, v[136:139], s[22:23] offset:3072 nt
	s_add_u32 s22, s22, s25
	s_addc_u32 s23, s23, 0
	global_load_dwordx2 v[80:81], v3, s[20:21] nt
	global_load_dwordx2 v[82:83], v3, s[20:21] offset:512 nt
	global_load_dwordx2 v[84:85], v3, s[20:21] offset:1024 nt
	global_load_dwordx2 v[86:87], v3, s[20:21] offset:1536 nt
	s_add_u32 s20, s20, s24
	s_addc_u32 s21, s21, 0
	global_load_dwordx2 v[88:89], v3, s[20:21] nt
	global_load_dwordx2 v[90:91], v3, s[20:21] offset:512 nt
	global_load_dwordx2 v[92:93], v3, s[20:21] offset:1024 nt
	global_load_dwordx2 v[94:95], v3, s[20:21] offset:1536 nt
	s_add_u32 s20, s20, s24
	s_addc_u32 s21, s21, 0
	global_load_dwordx2 v[96:97], v3, s[20:21] nt
	global_load_dwordx2 v[98:99], v3, s[20:21] offset:512 nt
	global_load_dwordx2 v[100:101], v3, s[20:21] offset:1024 nt
	global_load_dwordx2 v[102:103], v3, s[20:21] offset:1536 nt
	s_add_u32 s20, s20, s24
	s_addc_u32 s21, s21, 0
	global_load_dwordx2 v[104:105], v3, s[20:21] nt
	global_load_dwordx2 v[106:107], v3, s[20:21] offset:512 nt
	global_load_dwordx2 v[108:109], v3, s[20:21] offset:1024 nt
	global_load_dwordx2 v[110:111], v3, s[20:21] offset:1536 nt
	s_add_u32 s20, s20, s24
	s_addc_u32 s21, s21, 0
	s_waitcnt vmcnt(32)
	v_readlane_b32 s26, v16, 24
	v_lshlrev_b32_e32 v120, 16, v48
	v_and_b32_e32 v121, 0xffff0000, v48
	v_lshlrev_b32_e32 v122, 16, v49
	v_and_b32_e32 v123, 0xffff0000, v49
	v_mul_f32_e32 v120, s26, v120
	v_mul_f32_e32 v121, s26, v121
	v_mul_f32_e32 v122, s26, v122
	v_mul_f32_e32 v123, s26, v123
	v_mul_f32_e32 v124, v120, v32
	v_mul_f32_e32 v125, v121, v33
	v_mul_f32_e32 v126, v122, v34
	v_mul_f32_e32 v127, v123, v35
	global_store_dwordx4 v2, v[124:127], s[22:23] nt
	v_lshlrev_b32_e32 v120, 16, v50
	v_and_b32_e32 v121, 0xffff0000, v50
	v_lshlrev_b32_e32 v122, 16, v51
	v_and_b32_e32 v123, 0xffff0000, v51
	v_mul_f32_e32 v120, s26, v120
	v_mul_f32_e32 v121, s26, v121
	v_mul_f32_e32 v122, s26, v122
	v_mul_f32_e32 v123, s26, v123
	v_mul_f32_e32 v128, v120, v36
	v_mul_f32_e32 v129, v121, v37
	v_mul_f32_e32 v130, v122, v38
	v_mul_f32_e32 v131, v123, v39
	global_store_dwordx4 v2, v[128:131], s[22:23] offset:1024 nt
	v_lshlrev_b32_e32 v120, 16, v52
	v_and_b32_e32 v121, 0xffff0000, v52
	v_lshlrev_b32_e32 v122, 16, v53
	v_and_b32_e32 v123, 0xffff0000, v53
	v_mul_f32_e32 v120, s26, v120
	v_mul_f32_e32 v121, s26, v121
	v_mul_f32_e32 v122, s26, v122
	v_mul_f32_e32 v123, s26, v123
	v_mul_f32_e32 v132, v120, v40
	v_mul_f32_e32 v133, v121, v41
	v_mul_f32_e32 v134, v122, v42
	v_mul_f32_e32 v135, v123, v43
	global_store_dwordx4 v2, v[132:135], s[22:23] offset:2048 nt
	v_lshlrev_b32_e32 v120, 16, v54
	v_and_b32_e32 v121, 0xffff0000, v54
	v_lshlrev_b32_e32 v122, 16, v55
	v_and_b32_e32 v123, 0xffff0000, v55
	v_mul_f32_e32 v120, s26, v120
	v_mul_f32_e32 v121, s26, v121
	v_mul_f32_e32 v122, s26, v122
	v_mul_f32_e32 v123, s26, v123
	v_mul_f32_e32 v136, v120, v44
	v_mul_f32_e32 v137, v121, v45
	v_mul_f32_e32 v138, v122, v46
	v_mul_f32_e32 v139, v123, v47
	global_store_dwordx4 v2, v[136:139], s[22:23] offset:3072 nt
	s_add_u32 s22, s22, s25
	s_addc_u32 s23, s23, 0
	v_readlane_b32 s26, v16, 25
	v_lshlrev_b32_e32 v120, 16, v56
	v_and_b32_e32 v121, 0xffff0000, v56
	v_lshlrev_b32_e32 v122, 16, v57
	v_and_b32_e32 v123, 0xffff0000, v57
	v_mul_f32_e32 v120, s26, v120
	v_mul_f32_e32 v121, s26, v121
	v_mul_f32_e32 v122, s26, v122
	v_mul_f32_e32 v123, s26, v123
	v_mul_f32_e32 v124, v120, v32
	v_mul_f32_e32 v125, v121, v33
	v_mul_f32_e32 v126, v122, v34
	v_mul_f32_e32 v127, v123, v35
	global_store_dwordx4 v2, v[124:127], s[22:23] nt
	v_lshlrev_b32_e32 v120, 16, v58
	v_and_b32_e32 v121, 0xffff0000, v58
	v_lshlrev_b32_e32 v122, 16, v59
	v_and_b32_e32 v123, 0xffff0000, v59
	v_mul_f32_e32 v120, s26, v120
	v_mul_f32_e32 v121, s26, v121
	v_mul_f32_e32 v122, s26, v122
	v_mul_f32_e32 v123, s26, v123
	v_mul_f32_e32 v128, v120, v36
	v_mul_f32_e32 v129, v121, v37
; __device__ __forceinline__ float bflo(unsigned w) { return __uint_as_float(w << 16); }
; __device__ __forceinline__ float bfhi(unsigned w) { return __uint_as_float(w & 0xffff0000u); }
; __global__ void __launch_bounds__(512, 2) fwd_megakernel(Args a) {
;     ...
;       for (int m = gw0; m < flim; m += fstep) { f32x4* orow = (f32x4*)(hres + (size_t)m * D) + ln;
;         v2u w[4]; const float rs = nrs;
; #pragma unroll
;         for (int j = 0; j < 4; ++j) w[j] = nw[j];
;         { const int mn = m + fstep; if (mn < flim) { const v2u* xr = (const v2u*)(HB + (size_t)mn * D) + ln; nrs = pg8::row_rstd(slots, mn);
; #pragma unroll
;             for (int j = 0; j < 4; ++j) nw[j] = __builtin_nontemporal_load(xr + 64 * j); } }
; #pragma unroll
;         for (int j = 0; j < 4; ++j) { const f32x4 gg = *((const f32x4*)fg + ln + 64 * j);
;             __builtin_nontemporal_store((f32x4){bflo(w[j].x), bfhi(w[j].x), bflo(w[j].y), bfhi(w[j].y)} * rs * gg, orow + 64 * j); } } }
	v_mul_f32_e32 v130, v122, v38
	v_mul_f32_e32 v131, v123, v39
	global_store_dwordx4 v2, v[128:131], s[22:23] offset:1024 nt
	v_lshlrev_b32_e32 v120, 16, v60
	v_and_b32_e32 v121, 0xffff0000, v60
	v_lshlrev_b32_e32 v122, 16, v61
	v_and_b32_e32 v123, 0xffff0000, v61
	v_mul_f32_e32 v120, s26, v120
	v_mul_f32_e32 v121, s26, v121
	v_mul_f32_e32 v122, s26, v122
	v_mul_f32_e32 v123, s26, v123
	v_mul_f32_e32 v132, v120, v40
	v_mul_f32_e32 v133, v121, v41
	v_mul_f32_e32 v134, v122, v42
	v_mul_f32_e32 v135, v123, v43
	global_store_dwordx4 v2, v[132:135], s[22:23] offset:2048 nt
	v_lshlrev_b32_e32 v120, 16, v62
	v_and_b32_e32 v121, 0xffff0000, v62
	v_lshlrev_b32_e32 v122, 16, v63
	v_and_b32_e32 v123, 0xffff0000, v63
	v_mul_f32_e32 v120, s26, v120
	v_mul_f32_e32 v121, s26, v121
	v_mul_f32_e32 v122, s26, v122
	v_mul_f32_e32 v123, s26, v123
	v_mul_f32_e32 v136, v120, v44
	v_mul_f32_e32 v137, v121, v45
	v_mul_f32_e32 v138, v122, v46
	v_mul_f32_e32 v139, v123, v47
	global_store_dwordx4 v2, v[136:139], s[22:23] offset:3072 nt
	s_add_u32 s22, s22, s25
	s_addc_u32 s23, s23, 0
	v_readlane_b32 s26, v16, 26
	v_lshlrev_b32_e32 v120, 16, v64
	v_and_b32_e32 v121, 0xffff0000, v64
	v_lshlrev_b32_e32 v122, 16, v65
	v_and_b32_e32 v123, 0xffff0000, v65
	v_mul_f32_e32 v120, s26, v120
	v_mul_f32_e32 v121, s26, v121
	v_mul_f32_e32 v122, s26, v122
	v_mul_f32_e32 v123, s26, v123
	v_mul_f32_e32 v124, v120, v32
	v_mul_f32_e32 v125, v121, v33
	v_mul_f32_e32 v126, v122, v34
	v_mul_f32_e32 v127, v123, v35
	global_store_dwordx4 v2, v[124:127], s[22:23] nt
	v_lshlrev_b32_e32 v120, 16, v66
	v_and_b32_e32 v121, 0xffff0000, v66
	v_lshlrev_b32_e32 v122, 16, v67
	v_and_b32_e32 v123, 0xffff0000, v67
	v_mul_f32_e32 v120, s26, v120
	v_mul_f32_e32 v121, s26, v121
	v_mul_f32_e32 v122, s26, v122
	v_mul_f32_e32 v123, s26, v123
	v_mul_f32_e32 v128, v120, v36
	v_mul_f32_e32 v129, v121, v37
	v_mul_f32_e32 v130, v122, v38
	v_mul_f32_e32 v131, v123, v39
	global_store_dwordx4 v2, v[128:131], s[22:23] offset:1024 nt
	v_lshlrev_b32_e32 v120, 16, v68
	v_and_b32_e32 v121, 0xffff0000, v68
	v_lshlrev_b32_e32 v122, 16, v69
	v_and_b32_e32 v123, 0xffff0000, v69
	v_mul_f32_e32 v120, s26, v120
	v_mul_f32_e32 v121, s26, v121
	v_mul_f32_e32 v122, s26, v122
	v_mul_f32_e32 v123, s26, v123
	v_mul_f32_e32 v132, v120, v40
	v_mul_f32_e32 v133, v121, v41
	v_mul_f32_e32 v134, v122, v42
	v_mul_f32_e32 v135, v123, v43
	global_store_dwordx4 v2, v[132:135], s[22:23] offset:2048 nt
	v_lshlrev_b32_e32 v120, 16, v70
	v_and_b32_e32 v121, 0xffff0000, v70
	v_lshlrev_b32_e32 v122, 16, v71
	v_and_b32_e32 v123, 0xffff0000, v71
	v_mul_f32_e32 v120, s26, v120
	v_mul_f32_e32 v121, s26, v121
	v_mul_f32_e32 v122, s26, v122
	v_mul_f32_e32 v123, s26, v123
	v_mul_f32_e32 v136, v120, v44
	v_mul_f32_e32 v137, v121, v45
	v_mul_f32_e32 v138, v122, v46
	v_mul_f32_e32 v139, v123, v47
	global_store_dwordx4 v2, v[136:139], s[22:23] offset:3072 nt
	s_add_u32 s22, s22, s25
	s_addc_u32 s23, s23, 0
	v_readlane_b32 s26, v16, 27
	v_lshlrev_b32_e32 v120, 16, v72
	v_and_b32_e32 v121, 0xffff0000, v72
	v_lshlrev_b32_e32 v122, 16, v73
	v_and_b32_e32 v123, 0xffff0000, v73
	v_mul_f32_e32 v120, s26, v120
	v_mul_f32_e32 v121, s26, v121
	v_mul_f32_e32 v122, s26, v122
	v_mul_f32_e32 v123, s26, v123
	v_mul_f32_e32 v124, v120, v32
	v_mul_f32_e32 v125, v121, v33
	v_mul_f32_e32 v126, v122, v34
	v_mul_f32_e32 v127, v123, v35
	global_store_dwordx4 v2, v[124:127], s[22:23] nt
	v_lshlrev_b32_e32 v120, 16, v74
	v_and_b32_e32 v121, 0xffff0000, v74
	v_lshlrev_b32_e32 v122, 16, v75
	v_and_b32_e32 v123, 0xffff0000, v75
	v_mul_f32_e32 v120, s26, v120
	v_mul_f32_e32 v121, s26, v121
	v_mul_f32_e32 v122, s26, v122
	v_mul_f32_e32 v123, s26, v123
	v_mul_f32_e32 v128, v120, v36
	v_mul_f32_e32 v129, v121, v37
	v_mul_f32_e32 v130, v122, v38
	v_mul_f32_e32 v131, v123, v39
	global_store_dwordx4 v2, v[128:131], s[22:23] offset:1024 nt
	v_lshlrev_b32_e32 v120, 16, v76
	v_and_b32_e32 v121, 0xffff0000, v76
	v_lshlrev_b32_e32 v122, 16, v77
	v_and_b32_e32 v123, 0xffff0000, v77
	v_mul_f32_e32 v120, s26, v120
	v_mul_f32_e32 v121, s26, v121
	v_mul_f32_e32 v122, s26, v122
	v_mul_f32_e32 v123, s26, v123
	v_mul_f32_e32 v132, v120, v40
	v_mul_f32_e32 v133, v121, v41
	v_mul_f32_e32 v134, v122, v42
	v_mul_f32_e32 v135, v123, v43
	global_store_dwordx4 v2, v[132:135], s[22:23] offset:2048 nt
	v_lshlrev_b32_e32 v120, 16, v78
	v_and_b32_e32 v121, 0xffff0000, v78
	v_lshlrev_b32_e32 v122, 16, v79
	v_and_b32_e32 v123, 0xffff0000, v79
	v_mul_f32_e32 v120, s26, v120
	v_mul_f32_e32 v121, s26, v121
	v_mul_f32_e32 v122, s26, v122
	v_mul_f32_e32 v123, s26, v123
	v_mul_f32_e32 v136, v120, v44
	v_mul_f32_e32 v137, v121, v45
	v_mul_f32_e32 v138, v122, v46
	v_mul_f32_e32 v139, v123, v47
	global_store_dwordx4 v2, v[136:139], s[22:23] offset:3072 nt
	s_add_u32 s22, s22, s25
	s_addc_u32 s23, s23, 0
	s_waitcnt vmcnt(16)
; __device__ __forceinline__ float bflo(unsigned w) { return __uint_as_float(w << 16); }
; __device__ __forceinline__ float bfhi(unsigned w) { return __uint_as_float(w & 0xffff0000u); }
; __global__ void __launch_bounds__(512, 2) fwd_megakernel(Args a) {
;     ...
;       for (int m = gw0; m < flim; m += fstep) { f32x4* orow = (f32x4*)(hres + (size_t)m * D) + ln;
;         v2u w[4]; const float rs = nrs;
; #pragma unroll
;         for (int j = 0; j < 4; ++j) w[j] = nw[j];
;         { const int mn = m + fstep; if (mn < flim) { const v2u* xr = (const v2u*)(HB + (size_t)mn * D) + ln; nrs = pg8::row_rstd(slots, mn);
; #pragma unroll
;             for (int j = 0; j < 4; ++j) nw[j] = __builtin_nontemporal_load(xr + 64 * j); } }
; #pragma unroll
;         for (int j = 0; j < 4; ++j) { const f32x4 gg = *((const f32x4*)fg + ln + 64 * j);
;             __builtin_nontemporal_store((f32x4){bflo(w[j].x), bfhi(w[j].x), bflo(w[j].y), bfhi(w[j].y)} * rs * gg, orow + 64 * j); } } }
	v_readlane_b32 s26, v16, 28
	v_lshlrev_b32_e32 v120, 16, v80
	v_and_b32_e32 v121, 0xffff0000, v80
	v_lshlrev_b32_e32 v122, 16, v81
	v_and_b32_e32 v123, 0xffff0000, v81
	v_mul_f32_e32 v120, s26, v120
	v_mul_f32_e32 v121, s26, v121
	v_mul_f32_e32 v122, s26, v122
	v_mul_f32_e32 v123, s26, v123
	v_mul_f32_e32 v124, v120, v32
	v_mul_f32_e32 v125, v121, v33
	v_mul_f32_e32 v126, v122, v34
	v_mul_f32_e32 v127, v123, v35
	global_store_dwordx4 v2, v[124:127], s[22:23] nt
	v_lshlrev_b32_e32 v120, 16, v82
	v_and_b32_e32 v121, 0xffff0000, v82
	v_lshlrev_b32_e32 v122, 16, v83
	v_and_b32_e32 v123, 0xffff0000, v83
	v_mul_f32_e32 v120, s26, v120
	v_mul_f32_e32 v121, s26, v121
	v_mul_f32_e32 v122, s26, v122
	v_mul_f32_e32 v123, s26, v123
	v_mul_f32_e32 v128, v120, v36
	v_mul_f32_e32 v129, v121, v37
	v_mul_f32_e32 v130, v122, v38
	v_mul_f32_e32 v131, v123, v39
	global_store_dwordx4 v2, v[128:131], s[22:23] offset:1024 nt
	v_lshlrev_b32_e32 v120, 16, v84
	v_and_b32_e32 v121, 0xffff0000, v84
	v_lshlrev_b32_e32 v122, 16, v85
	v_and_b32_e32 v123, 0xffff0000, v85
	v_mul_f32_e32 v120, s26, v120
	v_mul_f32_e32 v121, s26, v121
	v_mul_f32_e32 v122, s26, v122
	v_mul_f32_e32 v123, s26, v123
	v_mul_f32_e32 v132, v120, v40
	v_mul_f32_e32 v133, v121, v41
	v_mul_f32_e32 v134, v122, v42
	v_mul_f32_e32 v135, v123, v43
	global_store_dwordx4 v2, v[132:135], s[22:23] offset:2048 nt
	v_lshlrev_b32_e32 v120, 16, v86
	v_and_b32_e32 v121, 0xffff0000, v86
	v_lshlrev_b32_e32 v122, 16, v87
	v_and_b32_e32 v123, 0xffff0000, v87
	v_mul_f32_e32 v120, s26, v120
	v_mul_f32_e32 v121, s26, v121
	v_mul_f32_e32 v122, s26, v122
	v_mul_f32_e32 v123, s26, v123
	v_mul_f32_e32 v136, v120, v44
	v_mul_f32_e32 v137, v121, v45
	v_mul_f32_e32 v138, v122, v46
	v_mul_f32_e32 v139, v123, v47
	global_store_dwordx4 v2, v[136:139], s[22:23] offset:3072 nt
	s_add_u32 s22, s22, s25
	s_addc_u32 s23, s23, 0
	v_readlane_b32 s26, v16, 29
	v_lshlrev_b32_e32 v120, 16, v88
	v_and_b32_e32 v121, 0xffff0000, v88
	v_lshlrev_b32_e32 v122, 16, v89
	v_and_b32_e32 v123, 0xffff0000, v89
	v_mul_f32_e32 v120, s26, v120
	v_mul_f32_e32 v121, s26, v121
	v_mul_f32_e32 v122, s26, v122
	v_mul_f32_e32 v123, s26, v123
	v_mul_f32_e32 v124, v120, v32
	v_mul_f32_e32 v125, v121, v33
	v_mul_f32_e32 v126, v122, v34
	v_mul_f32_e32 v127, v123, v35
	global_store_dwordx4 v2, v[124:127], s[22:23] nt
	v_lshlrev_b32_e32 v120, 16, v90
	v_and_b32_e32 v121, 0xffff0000, v90
	v_lshlrev_b32_e32 v122, 16, v91
	v_and_b32_e32 v123, 0xffff0000, v91
	v_mul_f32_e32 v120, s26, v120
	v_mul_f32_e32 v121, s26, v121
	v_mul_f32_e32 v122, s26, v122
	v_mul_f32_e32 v123, s26, v123
	v_mul_f32_e32 v128, v120, v36
	v_mul_f32_e32 v129, v121, v37
	v_mul_f32_e32 v130, v122, v38
	v_mul_f32_e32 v131, v123, v39
	global_store_dwordx4 v2, v[128:131], s[22:23] offset:1024 nt
	v_lshlrev_b32_e32 v120, 16, v92
	v_and_b32_e32 v121, 0xffff0000, v92
	v_lshlrev_b32_e32 v122, 16, v93
	v_and_b32_e32 v123, 0xffff0000, v93
	v_mul_f32_e32 v120, s26, v120
	v_mul_f32_e32 v121, s26, v121
	v_mul_f32_e32 v122, s26, v122
	v_mul_f32_e32 v123, s26, v123
	v_mul_f32_e32 v132, v120, v40
	v_mul_f32_e32 v133, v121, v41
	v_mul_f32_e32 v134, v122, v42
	v_mul_f32_e32 v135, v123, v43
	global_store_dwordx4 v2, v[132:135], s[22:23] offset:2048 nt
	v_lshlrev_b32_e32 v120, 16, v94
	v_and_b32_e32 v121, 0xffff0000, v94
	v_lshlrev_b32_e32 v122, 16, v95
	v_and_b32_e32 v123, 0xffff0000, v95
	v_mul_f32_e32 v120, s26, v120
	v_mul_f32_e32 v121, s26, v121
	v_mul_f32_e32 v122, s26, v122
	v_mul_f32_e32 v123, s26, v123
	v_mul_f32_e32 v136, v120, v44
	v_mul_f32_e32 v137, v121, v45
	v_mul_f32_e32 v138, v122, v46
	v_mul_f32_e32 v139, v123, v47
	global_store_dwordx4 v2, v[136:139], s[22:23] offset:3072 nt
	s_add_u32 s22, s22, s25
	s_addc_u32 s23, s23, 0
	v_readlane_b32 s26, v16, 30
	v_lshlrev_b32_e32 v120, 16, v96
	v_and_b32_e32 v121, 0xffff0000, v96
	v_lshlrev_b32_e32 v122, 16, v97
	v_and_b32_e32 v123, 0xffff0000, v97
	v_mul_f32_e32 v120, s26, v120
	v_mul_f32_e32 v121, s26, v121
	v_mul_f32_e32 v122, s26, v122
	v_mul_f32_e32 v123, s26, v123
	v_mul_f32_e32 v124, v120, v32
	v_mul_f32_e32 v125, v121, v33
	v_mul_f32_e32 v126, v122, v34
	v_mul_f32_e32 v127, v123, v35
	global_store_dwordx4 v2, v[124:127], s[22:23] nt
	v_lshlrev_b32_e32 v120, 16, v98
	v_and_b32_e32 v121, 0xffff0000, v98
	v_lshlrev_b32_e32 v122, 16, v99
	v_and_b32_e32 v123, 0xffff0000, v99
	v_mul_f32_e32 v120, s26, v120
	v_mul_f32_e32 v121, s26, v121
	v_mul_f32_e32 v122, s26, v122
	v_mul_f32_e32 v123, s26, v123
	v_mul_f32_e32 v128, v120, v36
	v_mul_f32_e32 v129, v121, v37
	v_mul_f32_e32 v130, v122, v38
	v_mul_f32_e32 v131, v123, v39
	global_store_dwordx4 v2, v[128:131], s[22:23] offset:1024 nt
	v_lshlrev_b32_e32 v120, 16, v100
	v_and_b32_e32 v121, 0xffff0000, v100
	v_lshlrev_b32_e32 v122, 16, v101
	v_and_b32_e32 v123, 0xffff0000, v101
	v_mul_f32_e32 v120, s26, v120
	v_mul_f32_e32 v121, s26, v121
	v_mul_f32_e32 v122, s26, v122
	v_mul_f32_e32 v123, s26, v123
; __device__ __forceinline__ float bflo(unsigned w) { return __uint_as_float(w << 16); }
; __device__ __forceinline__ float bfhi(unsigned w) { return __uint_as_float(w & 0xffff0000u); }
; #define lane (hw_lane())
; __global__ void __launch_bounds__(512, 2) fwd_megakernel(Args a) {
;     ...
;     { const float* fg = a.in[I_FING]; const int ln = lane, gw0 = grouped ? grp * SEQ + gj * 256 + wave * 32 : gw, fstep = grouped ? 1 : NGW, flim = grouped ? gw0 + 32 : M;
;       v2u nw[4]; float nrs = 0.f;
;       if (gw0 < flim) { const v2u* xr = (const v2u*)(HB + (size_t)gw0 * D) + ln; nrs = pg8::row_rstd(slots, gw0);
; #pragma unroll
;         for (int j = 0; j < 4; ++j) nw[j] = __builtin_nontemporal_load(xr + 64 * j); }
;       for (int m = gw0; m < flim; m += fstep) { f32x4* orow = (f32x4*)(hres + (size_t)m * D) + ln;
;         v2u w[4]; const float rs = nrs;
; #pragma unroll
;         for (int j = 0; j < 4; ++j) w[j] = nw[j];
;         { const int mn = m + fstep; if (mn < flim) { const v2u* xr = (const v2u*)(HB + (size_t)mn * D) + ln; nrs = pg8::row_rstd(slots, mn);
; #pragma unroll
;             for (int j = 0; j < 4; ++j) nw[j] = __builtin_nontemporal_load(xr + 64 * j); } }
; #pragma unroll
;         for (int j = 0; j < 4; ++j) { const f32x4 gg = *((const f32x4*)fg + ln + 64 * j);
;             __builtin_nontemporal_store((f32x4){bflo(w[j].x), bfhi(w[j].x), bflo(w[j].y), bfhi(w[j].y)} * rs * gg, orow + 64 * j); } } }
	v_mul_f32_e32 v132, v120, v40
	v_mul_f32_e32 v133, v121, v41
	v_mul_f32_e32 v134, v122, v42
	v_mul_f32_e32 v135, v123, v43
	global_store_dwordx4 v2, v[132:135], s[22:23] offset:2048 nt
	v_lshlrev_b32_e32 v120, 16, v102
	v_and_b32_e32 v121, 0xffff0000, v102
	v_lshlrev_b32_e32 v122, 16, v103
	v_and_b32_e32 v123, 0xffff0000, v103
	v_mul_f32_e32 v120, s26, v120
	v_mul_f32_e32 v121, s26, v121
	v_mul_f32_e32 v122, s26, v122
	v_mul_f32_e32 v123, s26, v123
	v_mul_f32_e32 v136, v120, v44
	v_mul_f32_e32 v137, v121, v45
	v_mul_f32_e32 v138, v122, v46
	v_mul_f32_e32 v139, v123, v47
	global_store_dwordx4 v2, v[136:139], s[22:23] offset:3072 nt
	s_add_u32 s22, s22, s25
	s_addc_u32 s23, s23, 0
	v_readlane_b32 s26, v16, 31
	v_lshlrev_b32_e32 v120, 16, v104
	v_and_b32_e32 v121, 0xffff0000, v104
	v_lshlrev_b32_e32 v122, 16, v105
	v_and_b32_e32 v123, 0xffff0000, v105
	v_mul_f32_e32 v120, s26, v120
	v_mul_f32_e32 v121, s26, v121
	v_mul_f32_e32 v122, s26, v122
	v_mul_f32_e32 v123, s26, v123
	v_mul_f32_e32 v124, v120, v32
	v_mul_f32_e32 v125, v121, v33
	v_mul_f32_e32 v126, v122, v34
	v_mul_f32_e32 v127, v123, v35
	global_store_dwordx4 v2, v[124:127], s[22:23] nt
	v_lshlrev_b32_e32 v120, 16, v106
	v_and_b32_e32 v121, 0xffff0000, v106
	v_lshlrev_b32_e32 v122, 16, v107
	v_and_b32_e32 v123, 0xffff0000, v107
	v_mul_f32_e32 v120, s26, v120
	v_mul_f32_e32 v121, s26, v121
	v_mul_f32_e32 v122, s26, v122
	v_mul_f32_e32 v123, s26, v123
	v_mul_f32_e32 v128, v120, v36
	v_mul_f32_e32 v129, v121, v37
	v_mul_f32_e32 v130, v122, v38
	v_mul_f32_e32 v131, v123, v39
	global_store_dwordx4 v2, v[128:131], s[22:23] offset:1024 nt
	v_lshlrev_b32_e32 v120, 16, v108
	v_and_b32_e32 v121, 0xffff0000, v108
	v_lshlrev_b32_e32 v122, 16, v109
	v_and_b32_e32 v123, 0xffff0000, v109
	v_mul_f32_e32 v120, s26, v120
	v_mul_f32_e32 v121, s26, v121
	v_mul_f32_e32 v122, s26, v122
	v_mul_f32_e32 v123, s26, v123
	v_mul_f32_e32 v132, v120, v40
	v_mul_f32_e32 v133, v121, v41
	v_mul_f32_e32 v134, v122, v42
	v_mul_f32_e32 v135, v123, v43
	global_store_dwordx4 v2, v[132:135], s[22:23] offset:2048 nt
	v_lshlrev_b32_e32 v120, 16, v110
	v_and_b32_e32 v121, 0xffff0000, v110
	v_lshlrev_b32_e32 v122, 16, v111
	v_and_b32_e32 v123, 0xffff0000, v111
	v_mul_f32_e32 v120, s26, v120
	v_mul_f32_e32 v121, s26, v121
	v_mul_f32_e32 v122, s26, v122
	v_mul_f32_e32 v123, s26, v123
	v_mul_f32_e32 v136, v120, v44
	v_mul_f32_e32 v137, v121, v45
	v_mul_f32_e32 v138, v122, v46
	v_mul_f32_e32 v139, v123, v47
	global_store_dwordx4 v2, v[136:139], s[22:23] offset:3072 nt
	s_add_u32 s22, s22, s25
	s_addc_u32 s23, s23, 0
	s_endpgm
.Lfn_generic:
	s_mov_b64 s[0:1], s[58:59]
	s_ashr_i32 s19, s18, 31
	s_lshl_b64 s[2:3], s[18:19], 11
	s_add_u32 s0, s0, s2
	s_addc_u32 s1, s1, s3
	s_mov_b64 s[2:3], s[58:59]
	s_lshl_b64 s[4:5], s[18:19], 6
	s_add_u32 s4, s2, s4
	s_addc_u32 s5, s3, s5
	s_mov_b32 s6, 0x5500000
	v_mov_b32_e32 v2, s4
	s_add_u32 s2, s4, 0x5500000
	v_mov_b32_e32 v3, s5
	v_add_co_u32_e32 v2, vcc, s6, v2
	s_addc_u32 s3, s5, 0
	s_nop 0
	v_addc_co_u32_e32 v3, vcc, 0, v3, vcc
	v_mov_b64_e32 v[4:5], s[2:3]
	flat_load_dwordx4 v[16:19], v[2:3]
	flat_load_dwordx4 v[20:23], v[4:5] offset:16
	flat_load_dwordx4 v[24:27], v[4:5] offset:32
	flat_load_dwordx4 v[28:31], v[4:5] offset:48
	v_ashrrev_i32_e32 v1, 31, v0
	v_lshlrev_b64 v[4:5], 3, v[0:1]
	v_lshl_add_u64 v[2:3], s[0:1], 0, v[4:5]
	s_mov_b32 s0, 0x7100000
	v_add_co_u32_e32 v10, vcc, s0, v2
	s_mov_b64 s[4:5], 0x7100000
	s_nop 0
	v_addc_co_u32_e32 v11, vcc, 0, v3, vcc
	v_lshl_add_u64 v[8:9], v[2:3], 0, s[4:5]
	flat_load_dwordx2 v[14:15], v[10:11] nt
	flat_load_dwordx2 v[12:13], v[8:9] offset:512 nt
	flat_load_dwordx2 v[6:7], v[8:9] offset:1024 nt
	flat_load_dwordx2 v[2:3], v[8:9] offset:1536 nt
	s_add_i32 s0, s18, s16
	s_ashr_i32 s1, s0, 31
	s_lshl_b64 s[2:3], s[0:1], 6
	s_add_u32 s9, s2, 0x5500000
	v_mov_b32_e32 v11, 0x358637bd
	s_addc_u32 s10, s3, 0
	s_ashr_i32 s17, s16, 31
	s_lshl_b64 s[2:3], s[0:1], 11
	s_lshl_b64 s[6:7], s[18:19], 12
	s_lshl_b64 s[0:1], s[16:17], 6
	v_lshl_add_u64 v[4:5], s[2:3], 0, v[4:5]
	s_lshl_b64 s[2:3], s[16:17], 11
	v_lshl_add_u64 v[4:5], v[4:5], 0, s[4:5]
	s_add_u32 s4, s56, s6
	v_lshlrev_b64 v[8:9], 4, v[0:1]
	s_addc_u32 s5, s57, s7
	v_lshl_add_u64 v[0:1], s[54:55], 0, v[8:9]
	v_lshl_add_u64 v[8:9], s[4:5], 0, v[8:9]
	s_mov_b64 s[4:5], 0xc00
	v_lshl_add_u64 v[8:9], v[8:9], 0, s[4:5]
	s_lshl_b64 s[4:5], s[16:17], 12
	s_waitcnt vmcnt(0) lgkmcnt(0)
	v_pk_add_f32 v[18:19], v[18:19], v[22:23]
	v_pk_add_f32 v[16:17], v[16:17], v[20:21]
	v_pk_add_f32 v[20:21], v[26:27], v[30:31]
	v_pk_add_f32 v[22:23], v[24:25], v[28:29]
	v_pk_add_f32 v[18:19], v[18:19], v[20:21]
	v_pk_add_f32 v[16:17], v[16:17], v[22:23]
	s_nop 0
	v_pk_mov_b32 v[20:21], v[16:17], v[18:19] op_sel:[1,0]
	v_mov_b32_e32 v17, v19
	v_pk_add_f32 v[16:17], v[20:21], v[16:17]
	s_nop 0
	v_add_f32_e32 v10, v16, v17
	v_fmamk_f32 v10, v10, 0x3a800000, v11
	v_rsq_f32_e32 v10, v10
	s_branch .LBB0_1118
